# ffn_in phases: per-tile row sum-of-squares load issued before the GEMM mainloop (kept in a spare VGPR) instead of load+wait in the epilogue
# speedup vs baseline: 1.0073x; 1.0013x over previous
; DI int tid_() { int t = threadIdx.x; asm volatile("" : "+v"(t)); return t; }
; #define GL1_(RA, RB, i) { RA[i] = *(const u32x4*)(ap + (aoff + (i) * astep)); if ((i) < NB) RB[(i) < NB ? (i) : 0] = *(const u32x4*)(bp + (boff + (i) * bstep)); }
; #define LS1_(RA, RB, ST, i) { char* sn_ = lds + (ST) * STAGE; *(u32x4*)(sn_ + wofs + (i) * 32 * LROW) = RA[i]; \
;                               if ((i) < NB) *(u32x4*)(sn_ + STAGE_OP + wofs + (i) * 32 * LROW) = RB[(i) < NB ? (i) : 0]; }
; template <int NJ> DI void gemm_mainloop_reg(const bf16_t* __restrict__ A, int lda, const bf16_t* __restrict__ Bt, int ldb, int K, f32x16 (&acc)[2][NJ], char* lds) {
;   const int tid = tid_(), lane = tid & 63, w = tid >> 6, wm = w >> 1, wn = w & 1;
;   const int lr = tid >> 3, lc = tid & 7;
;   const char* ap = (const char*)A;
;   const char* bp = (const char*)Bt;
;   const unsigned aoff = (unsigned)(lr * lda + lc * 8) * 2u, boff = (unsigned)(lr * ldb + lc * 8) * 2u;
;   const unsigned astep = (unsigned)(32 * lda) * 2u, bstep = (unsigned)(32 * ldb) * 2u;
;   constexpr int NB = 2 * NJ;
;   u32x4 ra0[4], rb0[NB], ra1[4], rb1[NB];
;   const int wofs = lr * LROW + lc * 16;
;   const int a_rd = (wm * 64 + (lane & 31)) * LROW + (lane >> 5) * 16;
;   const int b_rd = STAGE_OP + (wn * 32 * NJ + (lane & 31)) * LROW + (lane >> 5) * 16;
;     ...
; #pragma unroll
;   for (int i = 0; i < 4; ++i) GL1_(ra0, rb0, i);
;   ap += 128; bp += 128;
; #pragma unroll
;   for (int i = 0; i < 4; ++i) GL1_(ra1, rb1, i);
;   ap += 128; bp += 128;
; #pragma unroll
;   for (int i = 0; i < 4; ++i) LS1_(ra0, rb0, 0, i);
;   __syncthreads();
; DI void phase_ffn_in(const Ctx& c, const bf16_t* A, size_t woff, int site) {
;     ...
;   for (;;) {
;     const int j_ = grab_next(ctr, c.lds);
;     if (j_ >= 128 * 6) break;
;     const int mt = xcd_ * 16 + (j_ & 7) + 8 * ((j_ >> 6) & 1), nt = (j_ >> 7) * 8 + ((j_ >> 3) & 7);
;     if (nt >= 44) continue;
;     f32x16 acc[2][2]; zero_acc<2>(acc);
;     gemm_mainloop_reg<2>(A + (size_t)mt * 128 * LDX, LDX, Bt + (size_t)nt * 128 * LDX, LDX, DM, acc, c.lds);
;     acc_to_lds<2>(acc, cl);
;     if (tid < 128) rr[tid] = rsqrtf(ss[mt * 128 + tid] * (1.0f / DM) + EPS);
.LBB0_365:
	s_or_b64 exec, exec, s[2:3]
	s_add_i32 s24, 0, 0x12210
	s_cmp_lg_u32 s24, -1
	s_cselect_b32 s2, s24, 0
	s_cselect_b32 s3, s79, 0
	v_mov_b32_e32 v2, s2
	v_mov_b32_e32 v3, s3
	s_waitcnt lgkmcnt(0)
	s_barrier
	flat_load_dword v2, v[2:3] sc0 sc1
	s_waitcnt vmcnt(0)
	s_mov_b64 s[2:3], -1
	s_waitcnt lgkmcnt(0)
	s_barrier
	v_readfirstlane_b32 s4, v2
	s_cmpk_gt_i32 s4, 0x2ff
	s_cbranch_scc1 .LBB0_360
	s_ashr_i32 s2, s4, 4
	s_and_b32 s2, s2, -8
	s_bfe_u32 s3, s4, 0x30003
	s_or_b32 s6, s2, s3
	s_cmp_gt_i32 s6, 43
	s_cbranch_scc1 .LBB0_359
	s_lshr_b32 s2, s4, 3
	s_and_b32 s7, s4, 7
	s_and_b32 s27, s2, 8
	s_or_b32 s2, s7, s27
	v_readlane_b32 s3, v250, 20
	s_or_b32 s34, s2, s3
	v_readlane_b32 s100, v248, 14
	v_readlane_b32 s101, v248, 15
	v_and_b32_e32 v254, 0x7f, v68
	v_lshl_add_u32 v254, s34, 7, v254
	v_ashrrev_i32_e32 v255, 31, v254
	v_lshl_add_u64 v[254:255], v[254:255], 2, s[100:101]
	global_load_dword v253, v[254:255], off
	s_nop 0
	v_mov_b32_e32 v34, v199
	s_mul_i32 s2, s34, 0x44000
	s_add_u32 s2, s25, s2
	v_ashrrev_i32_e32 v35, 3, v34
	v_lshlrev_b32_e32 v2, 4, v34
	v_and_b32_e32 v36, 0x70, v2
	v_mul_lo_u32 v2, v35, s9
	s_addc_u32 s3, s26, 0
	s_mul_i32 s4, s6, 0x44000
	v_or_b32_e32 v80, v36, v2
	s_mul_hi_i32 s5, s6, 0x44000
	s_add_u32 s4, s22, s4
	v_add_u32_e32 v79, 0x11000, v80
	v_add_u32_e32 v78, 0x22000, v80
	v_add_u32_e32 v77, 0x33000, v80
	s_addc_u32 s5, s23, s5
	global_load_dwordx4 v[2:5], v80, s[2:3]
	global_load_dwordx4 v[6:9], v79, s[2:3]
	global_load_dwordx4 v[10:13], v78, s[2:3]
	global_load_dwordx4 v[14:17], v77, s[2:3]
	global_load_dwordx4 v[18:21], v80, s[4:5]
	global_load_dwordx4 v[22:25], v79, s[4:5]
	global_load_dwordx4 v[26:29], v78, s[4:5]
	global_load_dwordx4 v[30:33], v77, s[4:5]
	v_mul_lo_u32 v35, v35, s16
	v_lshrrev_b32_e32 v37, 1, v34
	v_and_b32_e32 v38, 31, v34
	v_add3_u32 v75, v35, v36, 0
	v_and_b32_e32 v39, 16, v37
	v_and_or_b32 v37, v37, s17, v38
	global_load_dwordx4 v[82:85], v80, s[2:3] offset:128
	global_load_dwordx4 v[86:89], v79, s[2:3] offset:128
	global_load_dwordx4 v[90:93], v78, s[2:3] offset:128
	global_load_dwordx4 v[94:97], v77, s[2:3] offset:128
	global_load_dwordx4 v[98:101], v80, s[4:5] offset:128
	global_load_dwordx4 v[102:105], v79, s[4:5] offset:128
	global_load_dwordx4 v[106:109], v78, s[4:5] offset:128
	global_load_dwordx4 v[110:113], v77, s[4:5] offset:128
	v_mul_lo_u32 v35, v37, s16
	v_add3_u32 v73, v35, v39, 0
	v_add_u32_e32 v76, 0xd800, v75
	s_waitcnt vmcnt(15)
	ds_write_b128 v75, v[2:5]
	s_waitcnt vmcnt(14)
	ds_write_b128 v75, v[6:9] offset:4608
	s_waitcnt vmcnt(13)
	ds_write_b128 v75, v[10:13] offset:9216
	s_waitcnt vmcnt(12)
	ds_write_b128 v75, v[14:17] offset:13824
	s_waitcnt vmcnt(11)
	ds_write_b128 v75, v[18:21] offset:18432
	s_waitcnt vmcnt(10)
	ds_write_b128 v75, v[22:25] offset:23040
	s_waitcnt vmcnt(9)
	ds_write_b128 v75, v[26:29] offset:27648
	s_waitcnt vmcnt(8)
	ds_write_b128 v75, v[30:33] offset:32256
	v_and_b32_e32 v2, 0x5f, v34
	v_mul_u32_u24_e32 v2, 0x90, v2
	v_add3_u32 v74, v2, v39, 0
	s_waitcnt lgkmcnt(0)
	s_barrier
	ds_read_b128 v[18:21], v73
	ds_read_b128 v[2:5], v74 offset:18432
	ds_read_b128 v[114:117], v73 offset:32
	ds_read_b128 v[118:121], v74 offset:18464
	ds_read_b128 v[22:25], v73 offset:4608
	ds_read_b128 v[122:125], v73 offset:4640
	ds_read_b128 v[26:29], v74 offset:23040
	ds_read_b128 v[126:129], v74 offset:23072
	global_load_dwordx4 v[130:133], v80, s[2:3] offset:256
	global_load_dwordx4 v[134:137], v80, s[4:5] offset:256
	s_waitcnt lgkmcnt(6)
	s_setprio 1
	s_nop 0
	v_mfma_f32_32x32x16_bf16 v[34:49], v[18:21], v[2:5], 0
	s_waitcnt vmcnt(9)
	ds_write_b128 v75, v[82:85] offset:36864
	s_waitcnt vmcnt(5)
	ds_write_b128 v75, v[98:101] offset:55296
	s_waitcnt lgkmcnt(5)
	v_mfma_f32_32x32x16_bf16 v[2:17], v[22:25], v[2:5], 0
	s_waitcnt lgkmcnt(3)
	v_mfma_f32_32x32x16_bf16 v[50:65], v[18:21], v[26:29], 0
	v_mfma_f32_32x32x16_bf16 v[18:33], v[22:25], v[26:29], 0
	global_load_dwordx4 v[82:85], v79, s[2:3] offset:256
	global_load_dwordx4 v[98:101], v79, s[4:5] offset:256
	v_mfma_f32_32x32x16_bf16 v[34:49], v[114:117], v[118:121], v[34:49]
	v_mfma_f32_32x32x16_bf16 v[2:17], v[122:125], v[118:121], v[2:17]
	s_waitcnt lgkmcnt(2)
	v_mfma_f32_32x32x16_bf16 v[50:65], v[114:117], v[126:129], v[50:65]
	ds_read_b128 v[114:117], v73 offset:64
	ds_read_b128 v[118:121], v73 offset:4672
	ds_read_b128 v[138:141], v74 offset:18496
	ds_read_b128 v[142:145], v74 offset:23104
	ds_write_b128 v75, v[86:89] offset:41472
	s_waitcnt vmcnt(6)
	ds_write_b128 v75, v[102:105] offset:59904
	v_mfma_f32_32x32x16_bf16 v[18:33], v[122:125], v[126:129], v[18:33]
	global_load_dwordx4 v[86:89], v78, s[2:3] offset:256
	global_load_dwordx4 v[102:105], v78, s[4:5] offset:256
	s_waitcnt lgkmcnt(3)
	v_mfma_f32_32x32x16_bf16 v[34:49], v[114:117], v[138:141], v[34:49]
	v_mfma_f32_32x32x16_bf16 v[2:17], v[118:121], v[138:141], v[2:17]
	s_waitcnt lgkmcnt(2)
	v_mfma_f32_32x32x16_bf16 v[50:65], v[114:117], v[142:145], v[50:65]
	ds_read_b128 v[114:117], v73 offset:96
	ds_read_b128 v[122:125], v73 offset:4704
	ds_read_b128 v[126:129], v74 offset:18528
	ds_read_b128 v[138:141], v74 offset:23136
	ds_write_b128 v75, v[90:93] offset:46080
	s_waitcnt vmcnt(7)
	ds_write_b128 v75, v[106:109] offset:64512
	v_mfma_f32_32x32x16_bf16 v[18:33], v[118:121], v[142:145], v[18:33]
	global_load_dwordx4 v[90:93], v77, s[2:3] offset:256
	global_load_dwordx4 v[106:109], v77, s[4:5] offset:256
	s_waitcnt lgkmcnt(3)
	v_mfma_f32_32x32x16_bf16 v[34:49], v[114:117], v[126:129], v[34:49]
	ds_write_b128 v75, v[94:97] offset:50688
	s_waitcnt vmcnt(8)
	ds_write_b128 v76, v[110:113] offset:13824
	v_mfma_f32_32x32x16_bf16 v[2:17], v[122:125], v[126:129], v[2:17]
	s_waitcnt lgkmcnt(4)
	v_mfma_f32_32x32x16_bf16 v[50:65], v[114:117], v[138:141], v[50:65]
	v_mfma_f32_32x32x16_bf16 v[18:33], v[122:125], v[138:141], v[18:33]
	s_waitcnt lgkmcnt(0)
	s_barrier
; #define GL1_(RA, RB, i) { RA[i] = *(const u32x4*)(ap + (aoff + (i) * astep)); if ((i) < NB) RB[(i) < NB ? (i) : 0] = *(const u32x4*)(bp + (boff + (i) * bstep)); }
; #define LS1_(RA, RB, ST, i) { char* sn_ = lds + (ST) * STAGE; *(u32x4*)(sn_ + wofs + (i) * 32 * LROW) = RA[i]; \
;                               if ((i) < NB) *(u32x4*)(sn_ + STAGE_OP + wofs + (i) * 32 * LROW) = RB[(i) < NB ? (i) : 0]; }
; template <int NJ> DI void gemm_mainloop_reg(const bf16_t* __restrict__ A, int lda, const bf16_t* __restrict__ Bt, int ldb, int K, f32x16 (&acc)[2][NJ], char* lds) {
;     ...
; #pragma unroll
;   for (int i = 0; i < 4; ++i) GL1_(ra0, rb0, i);
;   ap += 128; bp += 128;
; #pragma unroll
;   for (int i = 0; i < 4; ++i) GL1_(ra1, rb1, i);
;   ap += 128; bp += 128;
; #pragma unroll
;   for (int i = 0; i < 4; ++i) LS1_(ra0, rb0, 0, i);
;   __syncthreads();
;   const int nk = K >> 6;
;   for (int kt = 0; kt < nk; kt += 2) {
;     const bool l0 = (kt + 2 < nk), l1 = (kt + 3 < nk);
;     STEP_(0, l0, ra0, rb0, true, ra1, rb1);
;     __syncthreads();
;     STEP_(1, l1, ra1, rb1, l0, ra0, rb0);
;     __syncthreads();
	ds_read_b128 v[94:97], v73 offset:36864
	ds_read_b128 v[110:113], v74 offset:55296
	ds_read_b128 v[114:117], v73 offset:36896
	ds_read_b128 v[118:121], v74 offset:55328
	ds_read_b128 v[122:125], v73 offset:41472
	ds_read_b128 v[126:129], v73 offset:41504
	s_waitcnt lgkmcnt(4)
	v_mfma_f32_32x32x16_bf16 v[34:49], v[94:97], v[110:113], v[34:49]
	s_waitcnt lgkmcnt(1)
	v_mfma_f32_32x32x16_bf16 v[2:17], v[122:125], v[110:113], v[2:17]
	ds_read_b128 v[110:113], v74 offset:59904
	ds_read_b128 v[138:141], v74 offset:59936
	s_waitcnt lgkmcnt(1)
	v_mfma_f32_32x32x16_bf16 v[50:65], v[94:97], v[110:113], v[50:65]
	global_load_dwordx4 v[94:97], v80, s[2:3] offset:384
	global_load_dwordx4 v[142:145], v80, s[4:5] offset:384
	s_waitcnt vmcnt(9)
	ds_write_b128 v75, v[130:133]
	s_waitcnt vmcnt(8)
	ds_write_b128 v75, v[134:137] offset:18432
	v_mfma_f32_32x32x16_bf16 v[18:33], v[122:125], v[110:113], v[18:33]
	v_mfma_f32_32x32x16_bf16 v[34:49], v[114:117], v[118:121], v[34:49]
	s_waitcnt lgkmcnt(2)
	v_mfma_f32_32x32x16_bf16 v[50:65], v[114:117], v[138:141], v[50:65]
	global_load_dwordx4 v[110:113], v79, s[2:3] offset:384
	global_load_dwordx4 v[114:117], v79, s[4:5] offset:384
	v_mfma_f32_32x32x16_bf16 v[2:17], v[126:129], v[118:121], v[2:17]
	ds_read_b128 v[118:121], v73 offset:36928
	ds_read_b128 v[122:125], v73 offset:41536
	ds_read_b128 v[130:133], v74 offset:55360
	ds_read_b128 v[134:137], v74 offset:59968
	s_waitcnt vmcnt(9)
	ds_write_b128 v75, v[82:85] offset:4608
	s_waitcnt vmcnt(8)
	ds_write_b128 v75, v[98:101] offset:23040
	v_mfma_f32_32x32x16_bf16 v[18:33], v[126:129], v[138:141], v[18:33]
	global_load_dwordx4 v[82:85], v78, s[2:3] offset:384
	global_load_dwordx4 v[98:101], v78, s[4:5] offset:384
	s_waitcnt lgkmcnt(3)
	v_mfma_f32_32x32x16_bf16 v[34:49], v[118:121], v[130:133], v[34:49]
	v_mfma_f32_32x32x16_bf16 v[2:17], v[122:125], v[130:133], v[2:17]
	s_waitcnt lgkmcnt(2)
	v_mfma_f32_32x32x16_bf16 v[50:65], v[118:121], v[134:137], v[50:65]
	ds_read_b128 v[118:121], v73 offset:36960
	ds_read_b128 v[126:129], v73 offset:41568
	ds_read_b128 v[130:133], v74 offset:55392
	ds_read_b128 v[138:141], v74 offset:60000
	s_waitcnt vmcnt(9)
	ds_write_b128 v75, v[86:89] offset:9216
	s_waitcnt vmcnt(8)
	ds_write_b128 v75, v[102:105] offset:27648
	v_mfma_f32_32x32x16_bf16 v[18:33], v[122:125], v[134:137], v[18:33]
	global_load_dwordx4 v[86:89], v77, s[2:3] offset:384
	global_load_dwordx4 v[102:105], v77, s[4:5] offset:384
	s_waitcnt lgkmcnt(3)
	v_mfma_f32_32x32x16_bf16 v[34:49], v[118:121], v[130:133], v[34:49]
	s_waitcnt vmcnt(9)
	ds_write_b128 v75, v[90:93] offset:13824
	s_waitcnt vmcnt(8)
	ds_write_b128 v75, v[106:109] offset:32256
	v_mfma_f32_32x32x16_bf16 v[2:17], v[126:129], v[130:133], v[2:17]
	s_waitcnt lgkmcnt(4)
	v_mfma_f32_32x32x16_bf16 v[50:65], v[118:121], v[138:141], v[50:65]
	v_mfma_f32_32x32x16_bf16 v[18:33], v[126:129], v[138:141], v[18:33]
	s_waitcnt lgkmcnt(0)
	s_barrier
	ds_read_b128 v[90:93], v73
	ds_read_b128 v[106:109], v74 offset:18432
	ds_read_b128 v[118:121], v73 offset:32
	ds_read_b128 v[122:125], v74 offset:18464
	ds_read_b128 v[126:129], v73 offset:4608
	ds_read_b128 v[130:133], v73 offset:4640
	s_waitcnt lgkmcnt(4)
	v_mfma_f32_32x32x16_bf16 v[34:49], v[90:93], v[106:109], v[34:49]
	s_waitcnt lgkmcnt(1)
	v_mfma_f32_32x32x16_bf16 v[2:17], v[126:129], v[106:109], v[2:17]
	ds_read_b128 v[106:109], v74 offset:23040
	ds_read_b128 v[134:137], v74 offset:23072
	s_waitcnt lgkmcnt(1)
	v_mfma_f32_32x32x16_bf16 v[50:65], v[90:93], v[106:109], v[50:65]
	global_load_dwordx4 v[90:93], v80, s[2:3] offset:512
	global_load_dwordx4 v[138:141], v80, s[4:5] offset:512
	s_waitcnt vmcnt(9)
	ds_write_b128 v75, v[94:97] offset:36864
	s_waitcnt vmcnt(8)
	ds_write_b128 v75, v[142:145] offset:55296
	v_mfma_f32_32x32x16_bf16 v[18:33], v[126:129], v[106:109], v[18:33]
	global_load_dwordx4 v[94:97], v79, s[2:3] offset:512
	global_load_dwordx4 v[106:109], v79, s[4:5] offset:512
	v_mfma_f32_32x32x16_bf16 v[34:49], v[118:121], v[122:125], v[34:49]
	v_mfma_f32_32x32x16_bf16 v[2:17], v[130:133], v[122:125], v[2:17]
	s_waitcnt lgkmcnt(2)
	v_mfma_f32_32x32x16_bf16 v[50:65], v[118:121], v[134:137], v[50:65]
	ds_read_b128 v[118:121], v73 offset:64
	ds_read_b128 v[122:125], v73 offset:4672
	ds_read_b128 v[126:129], v74 offset:18496
	ds_read_b128 v[142:145], v74 offset:23104
	s_waitcnt vmcnt(9)
	ds_write_b128 v75, v[110:113] offset:41472
	s_waitcnt vmcnt(8)
	ds_write_b128 v75, v[114:117] offset:59904
	v_mfma_f32_32x32x16_bf16 v[18:33], v[130:133], v[134:137], v[18:33]
	global_load_dwordx4 v[110:113], v78, s[2:3] offset:512
	global_load_dwordx4 v[114:117], v78, s[4:5] offset:512
	s_waitcnt lgkmcnt(3)
	v_mfma_f32_32x32x16_bf16 v[34:49], v[118:121], v[126:129], v[34:49]
	v_mfma_f32_32x32x16_bf16 v[2:17], v[122:125], v[126:129], v[2:17]
	s_waitcnt lgkmcnt(2)
	v_mfma_f32_32x32x16_bf16 v[50:65], v[118:121], v[142:145], v[50:65]
	ds_read_b128 v[118:121], v73 offset:96
	ds_read_b128 v[126:129], v73 offset:4704
	ds_read_b128 v[130:133], v74 offset:18528
	ds_read_b128 v[134:137], v74 offset:23136
	s_waitcnt vmcnt(9)
	ds_write_b128 v75, v[82:85] offset:46080
	s_waitcnt vmcnt(8)
	ds_write_b128 v75, v[98:101] offset:64512
	v_mfma_f32_32x32x16_bf16 v[18:33], v[122:125], v[142:145], v[18:33]
	global_load_dwordx4 v[82:85], v77, s[2:3] offset:512
	global_load_dwordx4 v[98:101], v77, s[4:5] offset:512
	s_waitcnt lgkmcnt(3)
	v_mfma_f32_32x32x16_bf16 v[34:49], v[118:121], v[130:133], v[34:49]
	s_waitcnt vmcnt(9)
	ds_write_b128 v75, v[86:89] offset:50688
	s_waitcnt vmcnt(8)
	ds_write_b128 v76, v[102:105] offset:13824
	v_mfma_f32_32x32x16_bf16 v[2:17], v[126:129], v[130:133], v[2:17]
	s_waitcnt lgkmcnt(4)
	v_mfma_f32_32x32x16_bf16 v[50:65], v[118:121], v[134:137], v[50:65]
	v_mfma_f32_32x32x16_bf16 v[18:33], v[126:129], v[134:137], v[18:33]
	s_waitcnt lgkmcnt(0)
	s_barrier
; #define GL1_(RA, RB, i) { RA[i] = *(const u32x4*)(ap + (aoff + (i) * astep)); if ((i) < NB) RB[(i) < NB ? (i) : 0] = *(const u32x4*)(bp + (boff + (i) * bstep)); }
; #define LS1_(RA, RB, ST, i) { char* sn_ = lds + (ST) * STAGE; *(u32x4*)(sn_ + wofs + (i) * 32 * LROW) = RA[i]; \
;                               if ((i) < NB) *(u32x4*)(sn_ + STAGE_OP + wofs + (i) * 32 * LROW) = RB[(i) < NB ? (i) : 0]; }
; template <int NJ> DI void gemm_mainloop_reg(const bf16_t* __restrict__ A, int lda, const bf16_t* __restrict__ Bt, int ldb, int K, f32x16 (&acc)[2][NJ], char* lds) {
;     ...
; #pragma unroll
;   for (int i = 0; i < 4; ++i) GL1_(ra0, rb0, i);
;   ap += 128; bp += 128;
; #pragma unroll
;   for (int i = 0; i < 4; ++i) GL1_(ra1, rb1, i);
;   ap += 128; bp += 128;
; #pragma unroll
;   for (int i = 0; i < 4; ++i) LS1_(ra0, rb0, 0, i);
;   __syncthreads();
;   const int nk = K >> 6;
;   for (int kt = 0; kt < nk; kt += 2) {
;     const bool l0 = (kt + 2 < nk), l1 = (kt + 3 < nk);
;     STEP_(0, l0, ra0, rb0, true, ra1, rb1);
;     __syncthreads();
;     STEP_(1, l1, ra1, rb1, l0, ra0, rb0);
;     __syncthreads();
	ds_read_b128 v[86:89], v73 offset:36864
	ds_read_b128 v[102:105], v74 offset:55296
	ds_read_b128 v[118:121], v73 offset:36896
	ds_read_b128 v[122:125], v74 offset:55328
	ds_read_b128 v[126:129], v73 offset:41472
	ds_read_b128 v[130:133], v73 offset:41504
	s_waitcnt lgkmcnt(4)
	v_mfma_f32_32x32x16_bf16 v[34:49], v[86:89], v[102:105], v[34:49]
	s_waitcnt lgkmcnt(1)
	v_mfma_f32_32x32x16_bf16 v[2:17], v[126:129], v[102:105], v[2:17]
	ds_read_b128 v[102:105], v74 offset:59904
	ds_read_b128 v[134:137], v74 offset:59936
	s_waitcnt lgkmcnt(1)
	v_mfma_f32_32x32x16_bf16 v[50:65], v[86:89], v[102:105], v[50:65]
	global_load_dwordx4 v[86:89], v80, s[2:3] offset:640
	global_load_dwordx4 v[142:145], v80, s[4:5] offset:640
	s_waitcnt vmcnt(9)
	ds_write_b128 v75, v[90:93]
	s_waitcnt vmcnt(8)
	ds_write_b128 v75, v[138:141] offset:18432
	v_mfma_f32_32x32x16_bf16 v[18:33], v[126:129], v[102:105], v[18:33]
	global_load_dwordx4 v[90:93], v79, s[2:3] offset:640
	global_load_dwordx4 v[102:105], v79, s[4:5] offset:640
	v_mfma_f32_32x32x16_bf16 v[34:49], v[118:121], v[122:125], v[34:49]
	v_mfma_f32_32x32x16_bf16 v[2:17], v[130:133], v[122:125], v[2:17]
	s_waitcnt lgkmcnt(2)
	v_mfma_f32_32x32x16_bf16 v[50:65], v[118:121], v[134:137], v[50:65]
	ds_read_b128 v[118:121], v73 offset:36928
	ds_read_b128 v[122:125], v73 offset:41536
	ds_read_b128 v[126:129], v74 offset:55360
	ds_read_b128 v[138:141], v74 offset:59968
	s_waitcnt vmcnt(9)
	ds_write_b128 v75, v[94:97] offset:4608
	s_waitcnt vmcnt(8)
	ds_write_b128 v75, v[106:109] offset:23040
	v_mfma_f32_32x32x16_bf16 v[18:33], v[130:133], v[134:137], v[18:33]
	global_load_dwordx4 v[94:97], v78, s[2:3] offset:640
	global_load_dwordx4 v[106:109], v78, s[4:5] offset:640
	s_waitcnt lgkmcnt(3)
	v_mfma_f32_32x32x16_bf16 v[34:49], v[118:121], v[126:129], v[34:49]
	v_mfma_f32_32x32x16_bf16 v[2:17], v[122:125], v[126:129], v[2:17]
	s_waitcnt lgkmcnt(2)
	v_mfma_f32_32x32x16_bf16 v[50:65], v[118:121], v[138:141], v[50:65]
	ds_read_b128 v[118:121], v73 offset:36960
	ds_read_b128 v[126:129], v73 offset:41568
	ds_read_b128 v[130:133], v74 offset:55392
	ds_read_b128 v[134:137], v74 offset:60000
	s_waitcnt vmcnt(9)
	ds_write_b128 v75, v[110:113] offset:9216
	s_waitcnt vmcnt(8)
	ds_write_b128 v75, v[114:117] offset:27648
	v_mfma_f32_32x32x16_bf16 v[18:33], v[122:125], v[138:141], v[18:33]
	global_load_dwordx4 v[110:113], v77, s[2:3] offset:640
	global_load_dwordx4 v[114:117], v77, s[4:5] offset:640
	s_waitcnt lgkmcnt(3)
	v_mfma_f32_32x32x16_bf16 v[34:49], v[118:121], v[130:133], v[34:49]
	s_waitcnt vmcnt(9)
	ds_write_b128 v75, v[82:85] offset:13824
	s_waitcnt vmcnt(8)
	ds_write_b128 v75, v[98:101] offset:32256
	v_mfma_f32_32x32x16_bf16 v[2:17], v[126:129], v[130:133], v[2:17]
	s_waitcnt lgkmcnt(4)
	v_mfma_f32_32x32x16_bf16 v[50:65], v[118:121], v[134:137], v[50:65]
	v_mfma_f32_32x32x16_bf16 v[18:33], v[126:129], v[134:137], v[18:33]
	s_waitcnt lgkmcnt(0)
	s_barrier
	ds_read_b128 v[82:85], v73
	ds_read_b128 v[98:101], v74 offset:18432
	ds_read_b128 v[118:121], v73 offset:32
	ds_read_b128 v[122:125], v74 offset:18464
	ds_read_b128 v[126:129], v73 offset:4608
	ds_read_b128 v[130:133], v73 offset:4640
	s_waitcnt lgkmcnt(4)
	v_mfma_f32_32x32x16_bf16 v[34:49], v[82:85], v[98:101], v[34:49]
	s_waitcnt lgkmcnt(1)
	v_mfma_f32_32x32x16_bf16 v[2:17], v[126:129], v[98:101], v[2:17]
	ds_read_b128 v[98:101], v74 offset:23040
	ds_read_b128 v[134:137], v74 offset:23072
	s_waitcnt lgkmcnt(1)
	v_mfma_f32_32x32x16_bf16 v[50:65], v[82:85], v[98:101], v[50:65]
	global_load_dwordx4 v[82:85], v80, s[2:3] offset:768
	global_load_dwordx4 v[138:141], v80, s[4:5] offset:768
	s_waitcnt vmcnt(9)
	ds_write_b128 v75, v[86:89] offset:36864
	s_waitcnt vmcnt(8)
	ds_write_b128 v75, v[142:145] offset:55296
	v_mfma_f32_32x32x16_bf16 v[18:33], v[126:129], v[98:101], v[18:33]
	global_load_dwordx4 v[86:89], v79, s[2:3] offset:768
	global_load_dwordx4 v[98:101], v79, s[4:5] offset:768
	v_mfma_f32_32x32x16_bf16 v[34:49], v[118:121], v[122:125], v[34:49]
	v_mfma_f32_32x32x16_bf16 v[2:17], v[130:133], v[122:125], v[2:17]
	s_waitcnt lgkmcnt(2)
	v_mfma_f32_32x32x16_bf16 v[50:65], v[118:121], v[134:137], v[50:65]
	ds_read_b128 v[118:121], v73 offset:64
	ds_read_b128 v[122:125], v73 offset:4672
	ds_read_b128 v[126:129], v74 offset:18496
	ds_read_b128 v[142:145], v74 offset:23104
	s_waitcnt vmcnt(9)
	ds_write_b128 v75, v[90:93] offset:41472
	s_waitcnt vmcnt(8)
	ds_write_b128 v75, v[102:105] offset:59904
	v_mfma_f32_32x32x16_bf16 v[18:33], v[130:133], v[134:137], v[18:33]
	global_load_dwordx4 v[90:93], v78, s[2:3] offset:768
	global_load_dwordx4 v[102:105], v78, s[4:5] offset:768
	s_waitcnt lgkmcnt(3)
	v_mfma_f32_32x32x16_bf16 v[34:49], v[118:121], v[126:129], v[34:49]
	v_mfma_f32_32x32x16_bf16 v[2:17], v[122:125], v[126:129], v[2:17]
	s_waitcnt lgkmcnt(2)
	v_mfma_f32_32x32x16_bf16 v[50:65], v[118:121], v[142:145], v[50:65]
	ds_read_b128 v[118:121], v73 offset:96
	ds_read_b128 v[126:129], v73 offset:4704
	ds_read_b128 v[130:133], v74 offset:18528
	ds_read_b128 v[134:137], v74 offset:23136
	s_waitcnt vmcnt(9)
	ds_write_b128 v75, v[94:97] offset:46080
	s_waitcnt vmcnt(8)
	ds_write_b128 v75, v[106:109] offset:64512
	v_mfma_f32_32x32x16_bf16 v[18:33], v[122:125], v[142:145], v[18:33]
	global_load_dwordx4 v[94:97], v77, s[2:3] offset:768
	global_load_dwordx4 v[106:109], v77, s[4:5] offset:768
	s_waitcnt lgkmcnt(3)
	v_mfma_f32_32x32x16_bf16 v[34:49], v[118:121], v[130:133], v[34:49]
	s_waitcnt vmcnt(9)
	ds_write_b128 v75, v[110:113] offset:50688
	s_waitcnt vmcnt(8)
	ds_write_b128 v76, v[114:117] offset:13824
	v_mfma_f32_32x32x16_bf16 v[2:17], v[126:129], v[130:133], v[2:17]
	s_waitcnt lgkmcnt(4)
	v_mfma_f32_32x32x16_bf16 v[50:65], v[118:121], v[134:137], v[50:65]
	v_mfma_f32_32x32x16_bf16 v[18:33], v[126:129], v[134:137], v[18:33]
	s_waitcnt lgkmcnt(0)
	s_barrier
; #define GL1_(RA, RB, i) { RA[i] = *(const u32x4*)(ap + (aoff + (i) * astep)); if ((i) < NB) RB[(i) < NB ? (i) : 0] = *(const u32x4*)(bp + (boff + (i) * bstep)); }
; #define LS1_(RA, RB, ST, i) { char* sn_ = lds + (ST) * STAGE; *(u32x4*)(sn_ + wofs + (i) * 32 * LROW) = RA[i]; \
;                               if ((i) < NB) *(u32x4*)(sn_ + STAGE_OP + wofs + (i) * 32 * LROW) = RB[(i) < NB ? (i) : 0]; }
; template <int NJ> DI void gemm_mainloop_reg(const bf16_t* __restrict__ A, int lda, const bf16_t* __restrict__ Bt, int ldb, int K, f32x16 (&acc)[2][NJ], char* lds) {
;     ...
; #pragma unroll
;   for (int i = 0; i < 4; ++i) GL1_(ra0, rb0, i);
;   ap += 128; bp += 128;
; #pragma unroll
;   for (int i = 0; i < 4; ++i) GL1_(ra1, rb1, i);
;   ap += 128; bp += 128;
; #pragma unroll
;   for (int i = 0; i < 4; ++i) LS1_(ra0, rb0, 0, i);
;   __syncthreads();
;   const int nk = K >> 6;
;   for (int kt = 0; kt < nk; kt += 2) {
;     const bool l0 = (kt + 2 < nk), l1 = (kt + 3 < nk);
;     STEP_(0, l0, ra0, rb0, true, ra1, rb1);
;     __syncthreads();
;     STEP_(1, l1, ra1, rb1, l0, ra0, rb0);
;     __syncthreads();
	ds_read_b128 v[110:113], v73 offset:36864
	ds_read_b128 v[114:117], v74 offset:55296
	ds_read_b128 v[118:121], v73 offset:36896
	ds_read_b128 v[122:125], v74 offset:55328
	ds_read_b128 v[126:129], v73 offset:41472
	ds_read_b128 v[130:133], v73 offset:41504
	s_waitcnt lgkmcnt(4)
	v_mfma_f32_32x32x16_bf16 v[34:49], v[110:113], v[114:117], v[34:49]
	s_waitcnt lgkmcnt(1)
	v_mfma_f32_32x32x16_bf16 v[2:17], v[126:129], v[114:117], v[2:17]
	ds_read_b128 v[114:117], v74 offset:59904
	ds_read_b128 v[134:137], v74 offset:59936
	s_waitcnt lgkmcnt(1)
	v_mfma_f32_32x32x16_bf16 v[50:65], v[110:113], v[114:117], v[50:65]
	global_load_dwordx4 v[110:113], v80, s[2:3] offset:896
	global_load_dwordx4 v[142:145], v80, s[4:5] offset:896
	s_waitcnt vmcnt(9)
	ds_write_b128 v75, v[82:85]
	s_waitcnt vmcnt(8)
	ds_write_b128 v75, v[138:141] offset:18432
	v_mfma_f32_32x32x16_bf16 v[18:33], v[126:129], v[114:117], v[18:33]
	global_load_dwordx4 v[82:85], v79, s[2:3] offset:896
	global_load_dwordx4 v[114:117], v79, s[4:5] offset:896
	v_mfma_f32_32x32x16_bf16 v[34:49], v[118:121], v[122:125], v[34:49]
	v_mfma_f32_32x32x16_bf16 v[2:17], v[130:133], v[122:125], v[2:17]
	s_waitcnt lgkmcnt(2)
	v_mfma_f32_32x32x16_bf16 v[50:65], v[118:121], v[134:137], v[50:65]
	ds_read_b128 v[118:121], v73 offset:36928
	ds_read_b128 v[122:125], v73 offset:41536
	ds_read_b128 v[126:129], v74 offset:55360
	ds_read_b128 v[138:141], v74 offset:59968
	s_waitcnt vmcnt(9)
	ds_write_b128 v75, v[86:89] offset:4608
	s_waitcnt vmcnt(8)
	ds_write_b128 v75, v[98:101] offset:23040
	v_mfma_f32_32x32x16_bf16 v[18:33], v[130:133], v[134:137], v[18:33]
	global_load_dwordx4 v[86:89], v78, s[2:3] offset:896
	global_load_dwordx4 v[98:101], v78, s[4:5] offset:896
	s_waitcnt lgkmcnt(3)
	v_mfma_f32_32x32x16_bf16 v[34:49], v[118:121], v[126:129], v[34:49]
	v_mfma_f32_32x32x16_bf16 v[2:17], v[122:125], v[126:129], v[2:17]
	s_waitcnt lgkmcnt(2)
	v_mfma_f32_32x32x16_bf16 v[50:65], v[118:121], v[138:141], v[50:65]
	ds_read_b128 v[118:121], v73 offset:36960
	ds_read_b128 v[126:129], v73 offset:41568
	ds_read_b128 v[130:133], v74 offset:55392
	ds_read_b128 v[134:137], v74 offset:60000
	s_waitcnt vmcnt(9)
	ds_write_b128 v75, v[90:93] offset:9216
	s_waitcnt vmcnt(8)
	ds_write_b128 v75, v[102:105] offset:27648
	v_mfma_f32_32x32x16_bf16 v[18:33], v[122:125], v[138:141], v[18:33]
	global_load_dwordx4 v[90:93], v77, s[2:3] offset:896
	global_load_dwordx4 v[102:105], v77, s[4:5] offset:896
	s_waitcnt lgkmcnt(3)
	v_mfma_f32_32x32x16_bf16 v[34:49], v[118:121], v[130:133], v[34:49]
	s_waitcnt vmcnt(9)
	ds_write_b128 v75, v[94:97] offset:13824
	s_waitcnt vmcnt(8)
	ds_write_b128 v75, v[106:109] offset:32256
	v_mfma_f32_32x32x16_bf16 v[2:17], v[126:129], v[130:133], v[2:17]
	s_waitcnt lgkmcnt(4)
	v_mfma_f32_32x32x16_bf16 v[50:65], v[118:121], v[134:137], v[50:65]
	v_mfma_f32_32x32x16_bf16 v[18:33], v[126:129], v[134:137], v[18:33]
	s_waitcnt lgkmcnt(0)
	s_barrier
	ds_read_b128 v[94:97], v73
	ds_read_b128 v[106:109], v74 offset:18432
	ds_read_b128 v[118:121], v73 offset:32
	ds_read_b128 v[122:125], v74 offset:18464
	ds_read_b128 v[126:129], v73 offset:4608
	ds_read_b128 v[130:133], v73 offset:4640
	s_waitcnt lgkmcnt(4)
	v_mfma_f32_32x32x16_bf16 v[34:49], v[94:97], v[106:109], v[34:49]
	s_waitcnt lgkmcnt(1)
	v_mfma_f32_32x32x16_bf16 v[2:17], v[126:129], v[106:109], v[2:17]
	ds_read_b128 v[106:109], v74 offset:23040
	ds_read_b128 v[134:137], v74 offset:23072
	s_waitcnt lgkmcnt(1)
	v_mfma_f32_32x32x16_bf16 v[50:65], v[94:97], v[106:109], v[50:65]
	global_load_dwordx4 v[94:97], v80, s[2:3] offset:1024
	global_load_dwordx4 v[138:141], v80, s[4:5] offset:1024
	s_waitcnt vmcnt(9)
	ds_write_b128 v75, v[110:113] offset:36864
	s_waitcnt vmcnt(8)
	ds_write_b128 v75, v[142:145] offset:55296
	v_mfma_f32_32x32x16_bf16 v[18:33], v[126:129], v[106:109], v[18:33]
	global_load_dwordx4 v[106:109], v79, s[2:3] offset:1024
	global_load_dwordx4 v[110:113], v79, s[4:5] offset:1024
	v_mfma_f32_32x32x16_bf16 v[34:49], v[118:121], v[122:125], v[34:49]
	v_mfma_f32_32x32x16_bf16 v[2:17], v[130:133], v[122:125], v[2:17]
	s_waitcnt lgkmcnt(2)
	v_mfma_f32_32x32x16_bf16 v[50:65], v[118:121], v[134:137], v[50:65]
	ds_read_b128 v[118:121], v73 offset:64
	ds_read_b128 v[122:125], v73 offset:4672
	ds_read_b128 v[126:129], v74 offset:18496
	ds_read_b128 v[142:145], v74 offset:23104
	s_waitcnt vmcnt(9)
	ds_write_b128 v75, v[82:85] offset:41472
	s_waitcnt vmcnt(8)
	ds_write_b128 v75, v[114:117] offset:59904
	v_mfma_f32_32x32x16_bf16 v[18:33], v[130:133], v[134:137], v[18:33]
	global_load_dwordx4 v[82:85], v78, s[2:3] offset:1024
	global_load_dwordx4 v[114:117], v78, s[4:5] offset:1024
	s_waitcnt lgkmcnt(3)
	v_mfma_f32_32x32x16_bf16 v[34:49], v[118:121], v[126:129], v[34:49]
	v_mfma_f32_32x32x16_bf16 v[2:17], v[122:125], v[126:129], v[2:17]
	s_waitcnt lgkmcnt(2)
	v_mfma_f32_32x32x16_bf16 v[50:65], v[118:121], v[142:145], v[50:65]
	ds_read_b128 v[118:121], v73 offset:96
	ds_read_b128 v[126:129], v73 offset:4704
	ds_read_b128 v[130:133], v74 offset:18528
	ds_read_b128 v[134:137], v74 offset:23136
	s_waitcnt vmcnt(9)
	ds_write_b128 v75, v[86:89] offset:46080
	s_waitcnt vmcnt(8)
	ds_write_b128 v75, v[98:101] offset:64512
	v_mfma_f32_32x32x16_bf16 v[18:33], v[122:125], v[142:145], v[18:33]
	global_load_dwordx4 v[86:89], v77, s[2:3] offset:1024
	global_load_dwordx4 v[98:101], v77, s[4:5] offset:1024
	s_waitcnt lgkmcnt(3)
	v_mfma_f32_32x32x16_bf16 v[34:49], v[118:121], v[130:133], v[34:49]
	s_waitcnt vmcnt(9)
	ds_write_b128 v75, v[90:93] offset:50688
	s_waitcnt vmcnt(8)
	ds_write_b128 v76, v[102:105] offset:13824
	v_mfma_f32_32x32x16_bf16 v[2:17], v[126:129], v[130:133], v[2:17]
	s_waitcnt lgkmcnt(4)
	v_mfma_f32_32x32x16_bf16 v[50:65], v[118:121], v[134:137], v[50:65]
	v_mfma_f32_32x32x16_bf16 v[18:33], v[126:129], v[134:137], v[18:33]
	s_waitcnt lgkmcnt(0)
	s_barrier
; #define GL1_(RA, RB, i) { RA[i] = *(const u32x4*)(ap + (aoff + (i) * astep)); if ((i) < NB) RB[(i) < NB ? (i) : 0] = *(const u32x4*)(bp + (boff + (i) * bstep)); }
; #define LS1_(RA, RB, ST, i) { char* sn_ = lds + (ST) * STAGE; *(u32x4*)(sn_ + wofs + (i) * 32 * LROW) = RA[i]; \
;                               if ((i) < NB) *(u32x4*)(sn_ + STAGE_OP + wofs + (i) * 32 * LROW) = RB[(i) < NB ? (i) : 0]; }
; template <int NJ> DI void gemm_mainloop_reg(const bf16_t* __restrict__ A, int lda, const bf16_t* __restrict__ Bt, int ldb, int K, f32x16 (&acc)[2][NJ], char* lds) {
;     ...
; #pragma unroll
;   for (int i = 0; i < 4; ++i) GL1_(ra0, rb0, i);
;   ap += 128; bp += 128;
; #pragma unroll
;   for (int i = 0; i < 4; ++i) GL1_(ra1, rb1, i);
;   ap += 128; bp += 128;
; #pragma unroll
;   for (int i = 0; i < 4; ++i) LS1_(ra0, rb0, 0, i);
;   __syncthreads();
;   const int nk = K >> 6;
;   for (int kt = 0; kt < nk; kt += 2) {
;     const bool l0 = (kt + 2 < nk), l1 = (kt + 3 < nk);
;     STEP_(0, l0, ra0, rb0, true, ra1, rb1);
;     __syncthreads();
;     STEP_(1, l1, ra1, rb1, l0, ra0, rb0);
;     __syncthreads();
	ds_read_b128 v[90:93], v73 offset:36864
	ds_read_b128 v[102:105], v74 offset:55296
	ds_read_b128 v[118:121], v73 offset:36896
	ds_read_b128 v[122:125], v74 offset:55328
	ds_read_b128 v[126:129], v73 offset:41472
	ds_read_b128 v[130:133], v73 offset:41504
	s_waitcnt lgkmcnt(4)
	v_mfma_f32_32x32x16_bf16 v[34:49], v[90:93], v[102:105], v[34:49]
	s_waitcnt lgkmcnt(1)
	v_mfma_f32_32x32x16_bf16 v[2:17], v[126:129], v[102:105], v[2:17]
	ds_read_b128 v[102:105], v74 offset:59904
	ds_read_b128 v[134:137], v74 offset:59936
	s_waitcnt lgkmcnt(1)
	v_mfma_f32_32x32x16_bf16 v[50:65], v[90:93], v[102:105], v[50:65]
	global_load_dwordx4 v[90:93], v80, s[2:3] offset:1152
	global_load_dwordx4 v[142:145], v80, s[4:5] offset:1152
	s_waitcnt vmcnt(9)
	ds_write_b128 v75, v[94:97]
	s_waitcnt vmcnt(8)
	ds_write_b128 v75, v[138:141] offset:18432
	v_mfma_f32_32x32x16_bf16 v[18:33], v[126:129], v[102:105], v[18:33]
	global_load_dwordx4 v[94:97], v79, s[2:3] offset:1152
	global_load_dwordx4 v[102:105], v79, s[4:5] offset:1152
	v_mfma_f32_32x32x16_bf16 v[34:49], v[118:121], v[122:125], v[34:49]
	v_mfma_f32_32x32x16_bf16 v[2:17], v[130:133], v[122:125], v[2:17]
	s_waitcnt lgkmcnt(2)
	v_mfma_f32_32x32x16_bf16 v[50:65], v[118:121], v[134:137], v[50:65]
	ds_read_b128 v[118:121], v73 offset:36928
	ds_read_b128 v[122:125], v73 offset:41536
	ds_read_b128 v[126:129], v74 offset:55360
	ds_read_b128 v[138:141], v74 offset:59968
	s_waitcnt vmcnt(9)
	ds_write_b128 v75, v[106:109] offset:4608
	s_waitcnt vmcnt(8)
	ds_write_b128 v75, v[110:113] offset:23040
	v_mfma_f32_32x32x16_bf16 v[18:33], v[130:133], v[134:137], v[18:33]
	global_load_dwordx4 v[106:109], v78, s[2:3] offset:1152
	global_load_dwordx4 v[110:113], v78, s[4:5] offset:1152
	s_waitcnt lgkmcnt(3)
	v_mfma_f32_32x32x16_bf16 v[34:49], v[118:121], v[126:129], v[34:49]
	v_mfma_f32_32x32x16_bf16 v[2:17], v[122:125], v[126:129], v[2:17]
	s_waitcnt lgkmcnt(2)
	v_mfma_f32_32x32x16_bf16 v[50:65], v[118:121], v[138:141], v[50:65]
	ds_read_b128 v[118:121], v73 offset:36960
	ds_read_b128 v[126:129], v73 offset:41568
	ds_read_b128 v[130:133], v74 offset:55392
	ds_read_b128 v[134:137], v74 offset:60000
	s_waitcnt vmcnt(9)
	ds_write_b128 v75, v[82:85] offset:9216
	s_waitcnt vmcnt(8)
	ds_write_b128 v75, v[114:117] offset:27648
	v_mfma_f32_32x32x16_bf16 v[18:33], v[122:125], v[138:141], v[18:33]
	global_load_dwordx4 v[82:85], v77, s[2:3] offset:1152
	global_load_dwordx4 v[114:117], v77, s[4:5] offset:1152
	s_waitcnt lgkmcnt(3)
	v_mfma_f32_32x32x16_bf16 v[34:49], v[118:121], v[130:133], v[34:49]
	s_waitcnt vmcnt(9)
	ds_write_b128 v75, v[86:89] offset:13824
	s_waitcnt vmcnt(8)
	ds_write_b128 v75, v[98:101] offset:32256
	v_mfma_f32_32x32x16_bf16 v[2:17], v[126:129], v[130:133], v[2:17]
	s_waitcnt lgkmcnt(4)
	v_mfma_f32_32x32x16_bf16 v[50:65], v[118:121], v[134:137], v[50:65]
	v_mfma_f32_32x32x16_bf16 v[18:33], v[126:129], v[134:137], v[18:33]
	s_waitcnt lgkmcnt(0)
	s_barrier
	ds_read_b128 v[86:89], v73
	ds_read_b128 v[98:101], v74 offset:18432
	ds_read_b128 v[118:121], v73 offset:32
	ds_read_b128 v[122:125], v74 offset:18464
	ds_read_b128 v[126:129], v73 offset:4608
	ds_read_b128 v[130:133], v73 offset:4640
	s_waitcnt lgkmcnt(4)
	v_mfma_f32_32x32x16_bf16 v[34:49], v[86:89], v[98:101], v[34:49]
	s_waitcnt lgkmcnt(1)
	v_mfma_f32_32x32x16_bf16 v[2:17], v[126:129], v[98:101], v[2:17]
	ds_read_b128 v[98:101], v74 offset:23040
	ds_read_b128 v[134:137], v74 offset:23072
	s_waitcnt lgkmcnt(1)
	v_mfma_f32_32x32x16_bf16 v[50:65], v[86:89], v[98:101], v[50:65]
	global_load_dwordx4 v[86:89], v80, s[2:3] offset:1280
	global_load_dwordx4 v[138:141], v80, s[4:5] offset:1280
	s_waitcnt vmcnt(9)
	ds_write_b128 v75, v[90:93] offset:36864
	s_waitcnt vmcnt(8)
	ds_write_b128 v75, v[142:145] offset:55296
	v_mfma_f32_32x32x16_bf16 v[18:33], v[126:129], v[98:101], v[18:33]
	global_load_dwordx4 v[90:93], v79, s[2:3] offset:1280
	global_load_dwordx4 v[98:101], v79, s[4:5] offset:1280
	v_mfma_f32_32x32x16_bf16 v[34:49], v[118:121], v[122:125], v[34:49]
	v_mfma_f32_32x32x16_bf16 v[2:17], v[130:133], v[122:125], v[2:17]
	s_waitcnt lgkmcnt(2)
	v_mfma_f32_32x32x16_bf16 v[50:65], v[118:121], v[134:137], v[50:65]
	ds_read_b128 v[118:121], v73 offset:64
	ds_read_b128 v[122:125], v73 offset:4672
	ds_read_b128 v[126:129], v74 offset:18496
	ds_read_b128 v[142:145], v74 offset:23104
	s_waitcnt vmcnt(9)
	ds_write_b128 v75, v[94:97] offset:41472
	s_waitcnt vmcnt(8)
	ds_write_b128 v75, v[102:105] offset:59904
	v_mfma_f32_32x32x16_bf16 v[18:33], v[130:133], v[134:137], v[18:33]
	global_load_dwordx4 v[94:97], v78, s[2:3] offset:1280
	global_load_dwordx4 v[102:105], v78, s[4:5] offset:1280
	s_waitcnt lgkmcnt(3)
	v_mfma_f32_32x32x16_bf16 v[34:49], v[118:121], v[126:129], v[34:49]
	v_mfma_f32_32x32x16_bf16 v[2:17], v[122:125], v[126:129], v[2:17]
	s_waitcnt lgkmcnt(2)
	v_mfma_f32_32x32x16_bf16 v[50:65], v[118:121], v[142:145], v[50:65]
	ds_read_b128 v[118:121], v73 offset:96
	ds_read_b128 v[126:129], v73 offset:4704
	ds_read_b128 v[130:133], v74 offset:18528
	ds_read_b128 v[134:137], v74 offset:23136
	s_waitcnt vmcnt(9)
	ds_write_b128 v75, v[106:109] offset:46080
	s_waitcnt vmcnt(8)
	ds_write_b128 v75, v[110:113] offset:64512
	v_mfma_f32_32x32x16_bf16 v[18:33], v[122:125], v[142:145], v[18:33]
	global_load_dwordx4 v[106:109], v77, s[2:3] offset:1280
	global_load_dwordx4 v[110:113], v77, s[4:5] offset:1280
	s_waitcnt lgkmcnt(3)
	v_mfma_f32_32x32x16_bf16 v[34:49], v[118:121], v[130:133], v[34:49]
	s_waitcnt vmcnt(9)
	ds_write_b128 v75, v[82:85] offset:50688
	s_waitcnt vmcnt(8)
	ds_write_b128 v76, v[114:117] offset:13824
	v_mfma_f32_32x32x16_bf16 v[2:17], v[126:129], v[130:133], v[2:17]
	s_waitcnt lgkmcnt(4)
	v_mfma_f32_32x32x16_bf16 v[50:65], v[118:121], v[134:137], v[50:65]
	v_mfma_f32_32x32x16_bf16 v[18:33], v[126:129], v[134:137], v[18:33]
	s_waitcnt lgkmcnt(0)
	s_barrier
; #define GL1_(RA, RB, i) { RA[i] = *(const u32x4*)(ap + (aoff + (i) * astep)); if ((i) < NB) RB[(i) < NB ? (i) : 0] = *(const u32x4*)(bp + (boff + (i) * bstep)); }
; #define LS1_(RA, RB, ST, i) { char* sn_ = lds + (ST) * STAGE; *(u32x4*)(sn_ + wofs + (i) * 32 * LROW) = RA[i]; \
;                               if ((i) < NB) *(u32x4*)(sn_ + STAGE_OP + wofs + (i) * 32 * LROW) = RB[(i) < NB ? (i) : 0]; }
; template <int NJ> DI void gemm_mainloop_reg(const bf16_t* __restrict__ A, int lda, const bf16_t* __restrict__ Bt, int ldb, int K, f32x16 (&acc)[2][NJ], char* lds) {
;     ...
; #pragma unroll
;   for (int i = 0; i < 4; ++i) GL1_(ra0, rb0, i);
;   ap += 128; bp += 128;
; #pragma unroll
;   for (int i = 0; i < 4; ++i) GL1_(ra1, rb1, i);
;   ap += 128; bp += 128;
; #pragma unroll
;   for (int i = 0; i < 4; ++i) LS1_(ra0, rb0, 0, i);
;   __syncthreads();
;   const int nk = K >> 6;
;   for (int kt = 0; kt < nk; kt += 2) {
;     const bool l0 = (kt + 2 < nk), l1 = (kt + 3 < nk);
;     STEP_(0, l0, ra0, rb0, true, ra1, rb1);
;     __syncthreads();
;     STEP_(1, l1, ra1, rb1, l0, ra0, rb0);
;     __syncthreads();
	ds_read_b128 v[82:85], v73 offset:36864
	ds_read_b128 v[114:117], v74 offset:55296
	ds_read_b128 v[118:121], v73 offset:36896
	ds_read_b128 v[122:125], v74 offset:55328
	ds_read_b128 v[126:129], v73 offset:41472
	ds_read_b128 v[130:133], v73 offset:41504
	s_waitcnt lgkmcnt(4)
	v_mfma_f32_32x32x16_bf16 v[34:49], v[82:85], v[114:117], v[34:49]
	s_waitcnt lgkmcnt(1)
	v_mfma_f32_32x32x16_bf16 v[2:17], v[126:129], v[114:117], v[2:17]
	ds_read_b128 v[114:117], v74 offset:59904
	ds_read_b128 v[134:137], v74 offset:59936
	s_waitcnt lgkmcnt(1)
	v_mfma_f32_32x32x16_bf16 v[50:65], v[82:85], v[114:117], v[50:65]
	global_load_dwordx4 v[82:85], v80, s[2:3] offset:1408
	global_load_dwordx4 v[142:145], v80, s[4:5] offset:1408
	s_waitcnt vmcnt(9)
	ds_write_b128 v75, v[86:89]
	s_waitcnt vmcnt(8)
	ds_write_b128 v75, v[138:141] offset:18432
	v_mfma_f32_32x32x16_bf16 v[18:33], v[126:129], v[114:117], v[18:33]
	global_load_dwordx4 v[86:89], v79, s[2:3] offset:1408
	global_load_dwordx4 v[114:117], v79, s[4:5] offset:1408
	v_mfma_f32_32x32x16_bf16 v[34:49], v[118:121], v[122:125], v[34:49]
	v_mfma_f32_32x32x16_bf16 v[2:17], v[130:133], v[122:125], v[2:17]
	s_waitcnt lgkmcnt(2)
	v_mfma_f32_32x32x16_bf16 v[50:65], v[118:121], v[134:137], v[50:65]
	ds_read_b128 v[118:121], v73 offset:36928
	ds_read_b128 v[122:125], v73 offset:41536
	ds_read_b128 v[126:129], v74 offset:55360
	ds_read_b128 v[138:141], v74 offset:59968
	s_waitcnt vmcnt(9)
	ds_write_b128 v75, v[90:93] offset:4608
	s_waitcnt vmcnt(8)
	ds_write_b128 v75, v[98:101] offset:23040
	v_mfma_f32_32x32x16_bf16 v[18:33], v[130:133], v[134:137], v[18:33]
	global_load_dwordx4 v[90:93], v78, s[2:3] offset:1408
	global_load_dwordx4 v[98:101], v78, s[4:5] offset:1408
	s_waitcnt lgkmcnt(3)
	v_mfma_f32_32x32x16_bf16 v[34:49], v[118:121], v[126:129], v[34:49]
	v_mfma_f32_32x32x16_bf16 v[2:17], v[122:125], v[126:129], v[2:17]
	s_waitcnt lgkmcnt(2)
	v_mfma_f32_32x32x16_bf16 v[50:65], v[118:121], v[138:141], v[50:65]
	ds_read_b128 v[118:121], v73 offset:36960
	ds_read_b128 v[126:129], v73 offset:41568
	ds_read_b128 v[130:133], v74 offset:55392
	ds_read_b128 v[134:137], v74 offset:60000
	s_waitcnt vmcnt(9)
	ds_write_b128 v75, v[94:97] offset:9216
	s_waitcnt vmcnt(8)
	ds_write_b128 v75, v[102:105] offset:27648
	v_mfma_f32_32x32x16_bf16 v[18:33], v[122:125], v[138:141], v[18:33]
	global_load_dwordx4 v[94:97], v77, s[2:3] offset:1408
	global_load_dwordx4 v[102:105], v77, s[4:5] offset:1408
	s_waitcnt lgkmcnt(3)
	v_mfma_f32_32x32x16_bf16 v[34:49], v[118:121], v[130:133], v[34:49]
	s_waitcnt vmcnt(9)
	ds_write_b128 v75, v[106:109] offset:13824
	s_waitcnt vmcnt(8)
	ds_write_b128 v75, v[110:113] offset:32256
	v_mfma_f32_32x32x16_bf16 v[2:17], v[126:129], v[130:133], v[2:17]
	s_waitcnt lgkmcnt(4)
	v_mfma_f32_32x32x16_bf16 v[50:65], v[118:121], v[134:137], v[50:65]
	v_mfma_f32_32x32x16_bf16 v[18:33], v[126:129], v[134:137], v[18:33]
	s_waitcnt lgkmcnt(0)
	s_barrier
	ds_read_b128 v[106:109], v73
	ds_read_b128 v[110:113], v74 offset:18432
	ds_read_b128 v[118:121], v73 offset:32
	ds_read_b128 v[122:125], v74 offset:18464
	ds_read_b128 v[126:129], v73 offset:4608
	ds_read_b128 v[130:133], v73 offset:4640
	s_waitcnt lgkmcnt(4)
	v_mfma_f32_32x32x16_bf16 v[34:49], v[106:109], v[110:113], v[34:49]
	s_waitcnt lgkmcnt(1)
	v_mfma_f32_32x32x16_bf16 v[2:17], v[126:129], v[110:113], v[2:17]
	ds_read_b128 v[110:113], v74 offset:23040
	ds_read_b128 v[134:137], v74 offset:23072
	s_waitcnt lgkmcnt(1)
	v_mfma_f32_32x32x16_bf16 v[50:65], v[106:109], v[110:113], v[50:65]
	global_load_dwordx4 v[106:109], v80, s[2:3] offset:1536
	global_load_dwordx4 v[138:141], v80, s[4:5] offset:1536
	s_waitcnt vmcnt(9)
	ds_write_b128 v75, v[82:85] offset:36864
	s_waitcnt vmcnt(8)
	ds_write_b128 v75, v[142:145] offset:55296
	v_mfma_f32_32x32x16_bf16 v[18:33], v[126:129], v[110:113], v[18:33]
	global_load_dwordx4 v[82:85], v79, s[2:3] offset:1536
	global_load_dwordx4 v[110:113], v79, s[4:5] offset:1536
	v_mfma_f32_32x32x16_bf16 v[34:49], v[118:121], v[122:125], v[34:49]
	v_mfma_f32_32x32x16_bf16 v[2:17], v[130:133], v[122:125], v[2:17]
	s_waitcnt lgkmcnt(2)
	v_mfma_f32_32x32x16_bf16 v[50:65], v[118:121], v[134:137], v[50:65]
	ds_read_b128 v[118:121], v73 offset:64
	ds_read_b128 v[122:125], v73 offset:4672
	ds_read_b128 v[126:129], v74 offset:18496
	ds_read_b128 v[142:145], v74 offset:23104
	s_waitcnt vmcnt(9)
	ds_write_b128 v75, v[86:89] offset:41472
	s_waitcnt vmcnt(8)
	ds_write_b128 v75, v[114:117] offset:59904
	v_mfma_f32_32x32x16_bf16 v[18:33], v[130:133], v[134:137], v[18:33]
	global_load_dwordx4 v[86:89], v78, s[2:3] offset:1536
	global_load_dwordx4 v[114:117], v78, s[4:5] offset:1536
	s_waitcnt lgkmcnt(3)
	v_mfma_f32_32x32x16_bf16 v[34:49], v[118:121], v[126:129], v[34:49]
	v_mfma_f32_32x32x16_bf16 v[2:17], v[122:125], v[126:129], v[2:17]
	s_waitcnt lgkmcnt(2)
	v_mfma_f32_32x32x16_bf16 v[50:65], v[118:121], v[142:145], v[50:65]
	ds_read_b128 v[118:121], v73 offset:96
	ds_read_b128 v[126:129], v73 offset:4704
	ds_read_b128 v[130:133], v74 offset:18528
	ds_read_b128 v[134:137], v74 offset:23136
	s_waitcnt vmcnt(9)
	ds_write_b128 v75, v[90:93] offset:46080
	s_waitcnt vmcnt(8)
	ds_write_b128 v75, v[98:101] offset:64512
	v_mfma_f32_32x32x16_bf16 v[18:33], v[122:125], v[142:145], v[18:33]
	global_load_dwordx4 v[90:93], v77, s[2:3] offset:1536
	global_load_dwordx4 v[98:101], v77, s[4:5] offset:1536
	s_waitcnt lgkmcnt(3)
	v_mfma_f32_32x32x16_bf16 v[34:49], v[118:121], v[130:133], v[34:49]
	s_waitcnt vmcnt(9)
	ds_write_b128 v75, v[94:97] offset:50688
	s_waitcnt vmcnt(8)
	ds_write_b128 v76, v[102:105] offset:13824
	v_mfma_f32_32x32x16_bf16 v[2:17], v[126:129], v[130:133], v[2:17]
	s_waitcnt lgkmcnt(4)
	v_mfma_f32_32x32x16_bf16 v[50:65], v[118:121], v[134:137], v[50:65]
	v_mfma_f32_32x32x16_bf16 v[18:33], v[126:129], v[134:137], v[18:33]
	s_waitcnt lgkmcnt(0)
	s_barrier
; #define GL1_(RA, RB, i) { RA[i] = *(const u32x4*)(ap + (aoff + (i) * astep)); if ((i) < NB) RB[(i) < NB ? (i) : 0] = *(const u32x4*)(bp + (boff + (i) * bstep)); }
; #define LS1_(RA, RB, ST, i) { char* sn_ = lds + (ST) * STAGE; *(u32x4*)(sn_ + wofs + (i) * 32 * LROW) = RA[i]; \
;                               if ((i) < NB) *(u32x4*)(sn_ + STAGE_OP + wofs + (i) * 32 * LROW) = RB[(i) < NB ? (i) : 0]; }
; template <int NJ> DI void gemm_mainloop_reg(const bf16_t* __restrict__ A, int lda, const bf16_t* __restrict__ Bt, int ldb, int K, f32x16 (&acc)[2][NJ], char* lds) {
;     ...
; #pragma unroll
;   for (int i = 0; i < 4; ++i) GL1_(ra0, rb0, i);
;   ap += 128; bp += 128;
; #pragma unroll
;   for (int i = 0; i < 4; ++i) GL1_(ra1, rb1, i);
;   ap += 128; bp += 128;
; #pragma unroll
;   for (int i = 0; i < 4; ++i) LS1_(ra0, rb0, 0, i);
;   __syncthreads();
;   const int nk = K >> 6;
;   for (int kt = 0; kt < nk; kt += 2) {
;     const bool l0 = (kt + 2 < nk), l1 = (kt + 3 < nk);
;     STEP_(0, l0, ra0, rb0, true, ra1, rb1);
;     __syncthreads();
;     STEP_(1, l1, ra1, rb1, l0, ra0, rb0);
;     __syncthreads();
	ds_read_b128 v[94:97], v73 offset:36864
	ds_read_b128 v[102:105], v74 offset:55296
	ds_read_b128 v[118:121], v73 offset:36896
	ds_read_b128 v[122:125], v74 offset:55328
	ds_read_b128 v[126:129], v73 offset:41472
	ds_read_b128 v[130:133], v73 offset:41504
	s_waitcnt lgkmcnt(4)
	v_mfma_f32_32x32x16_bf16 v[34:49], v[94:97], v[102:105], v[34:49]
	s_waitcnt lgkmcnt(1)
	v_mfma_f32_32x32x16_bf16 v[2:17], v[126:129], v[102:105], v[2:17]
	ds_read_b128 v[102:105], v74 offset:59904
	ds_read_b128 v[134:137], v74 offset:59936
	s_waitcnt lgkmcnt(1)
	v_mfma_f32_32x32x16_bf16 v[50:65], v[94:97], v[102:105], v[50:65]
	global_load_dwordx4 v[94:97], v80, s[2:3] offset:1664
	global_load_dwordx4 v[142:145], v80, s[4:5] offset:1664
	s_waitcnt vmcnt(9)
	ds_write_b128 v75, v[106:109]
	s_waitcnt vmcnt(8)
	ds_write_b128 v75, v[138:141] offset:18432
	v_mfma_f32_32x32x16_bf16 v[18:33], v[126:129], v[102:105], v[18:33]
	global_load_dwordx4 v[102:105], v79, s[2:3] offset:1664
	global_load_dwordx4 v[106:109], v79, s[4:5] offset:1664
	v_mfma_f32_32x32x16_bf16 v[34:49], v[118:121], v[122:125], v[34:49]
	v_mfma_f32_32x32x16_bf16 v[2:17], v[130:133], v[122:125], v[2:17]
	s_waitcnt lgkmcnt(2)
	v_mfma_f32_32x32x16_bf16 v[50:65], v[118:121], v[134:137], v[50:65]
	ds_read_b128 v[118:121], v73 offset:36928
	ds_read_b128 v[122:125], v73 offset:41536
	ds_read_b128 v[126:129], v74 offset:55360
	ds_read_b128 v[138:141], v74 offset:59968
	s_waitcnt vmcnt(9)
	ds_write_b128 v75, v[82:85] offset:4608
	s_waitcnt vmcnt(8)
	ds_write_b128 v75, v[110:113] offset:23040
	v_mfma_f32_32x32x16_bf16 v[18:33], v[130:133], v[134:137], v[18:33]
	global_load_dwordx4 v[82:85], v78, s[2:3] offset:1664
	global_load_dwordx4 v[110:113], v78, s[4:5] offset:1664
	s_waitcnt lgkmcnt(3)
	v_mfma_f32_32x32x16_bf16 v[34:49], v[118:121], v[126:129], v[34:49]
	v_mfma_f32_32x32x16_bf16 v[2:17], v[122:125], v[126:129], v[2:17]
	s_waitcnt lgkmcnt(2)
	v_mfma_f32_32x32x16_bf16 v[50:65], v[118:121], v[138:141], v[50:65]
	ds_read_b128 v[118:121], v73 offset:36960
	ds_read_b128 v[126:129], v73 offset:41568
	ds_read_b128 v[130:133], v74 offset:55392
	ds_read_b128 v[134:137], v74 offset:60000
	s_waitcnt vmcnt(9)
	ds_write_b128 v75, v[86:89] offset:9216
	s_waitcnt vmcnt(8)
	ds_write_b128 v75, v[114:117] offset:27648
	v_mfma_f32_32x32x16_bf16 v[18:33], v[122:125], v[138:141], v[18:33]
	global_load_dwordx4 v[86:89], v77, s[2:3] offset:1664
	global_load_dwordx4 v[114:117], v77, s[4:5] offset:1664
	s_waitcnt lgkmcnt(3)
	v_mfma_f32_32x32x16_bf16 v[34:49], v[118:121], v[130:133], v[34:49]
	s_waitcnt vmcnt(9)
	ds_write_b128 v75, v[90:93] offset:13824
	s_waitcnt vmcnt(8)
	ds_write_b128 v75, v[98:101] offset:32256
	v_mfma_f32_32x32x16_bf16 v[2:17], v[126:129], v[130:133], v[2:17]
	s_waitcnt lgkmcnt(4)
	v_mfma_f32_32x32x16_bf16 v[50:65], v[118:121], v[134:137], v[50:65]
	v_mfma_f32_32x32x16_bf16 v[18:33], v[126:129], v[134:137], v[18:33]
	s_waitcnt lgkmcnt(0)
	s_barrier
	ds_read_b128 v[90:93], v73
	ds_read_b128 v[98:101], v74 offset:18432
	ds_read_b128 v[118:121], v73 offset:32
	ds_read_b128 v[122:125], v74 offset:18464
	ds_read_b128 v[126:129], v73 offset:4608
	ds_read_b128 v[130:133], v73 offset:4640
	s_waitcnt lgkmcnt(4)
	v_mfma_f32_32x32x16_bf16 v[34:49], v[90:93], v[98:101], v[34:49]
	s_waitcnt lgkmcnt(1)
	v_mfma_f32_32x32x16_bf16 v[2:17], v[126:129], v[98:101], v[2:17]
	ds_read_b128 v[98:101], v74 offset:23040
	ds_read_b128 v[134:137], v74 offset:23072
	s_waitcnt lgkmcnt(1)
	v_mfma_f32_32x32x16_bf16 v[50:65], v[90:93], v[98:101], v[50:65]
	global_load_dwordx4 v[90:93], v80, s[2:3] offset:1792
	global_load_dwordx4 v[138:141], v80, s[4:5] offset:1792
	s_waitcnt vmcnt(9)
	ds_write_b128 v75, v[94:97] offset:36864
	s_waitcnt vmcnt(8)
	ds_write_b128 v75, v[142:145] offset:55296
	v_mfma_f32_32x32x16_bf16 v[18:33], v[126:129], v[98:101], v[18:33]
	global_load_dwordx4 v[94:97], v79, s[2:3] offset:1792
	global_load_dwordx4 v[98:101], v79, s[4:5] offset:1792
	v_mfma_f32_32x32x16_bf16 v[34:49], v[118:121], v[122:125], v[34:49]
	v_mfma_f32_32x32x16_bf16 v[2:17], v[130:133], v[122:125], v[2:17]
	s_waitcnt lgkmcnt(2)
	v_mfma_f32_32x32x16_bf16 v[50:65], v[118:121], v[134:137], v[50:65]
	ds_read_b128 v[118:121], v73 offset:64
	ds_read_b128 v[122:125], v73 offset:4672
	ds_read_b128 v[126:129], v74 offset:18496
	ds_read_b128 v[142:145], v74 offset:23104
	s_waitcnt vmcnt(9)
	ds_write_b128 v75, v[102:105] offset:41472
	s_waitcnt vmcnt(8)
	ds_write_b128 v75, v[106:109] offset:59904
	v_mfma_f32_32x32x16_bf16 v[18:33], v[130:133], v[134:137], v[18:33]
	global_load_dwordx4 v[102:105], v78, s[2:3] offset:1792
	global_load_dwordx4 v[106:109], v78, s[4:5] offset:1792
	s_waitcnt lgkmcnt(3)
	v_mfma_f32_32x32x16_bf16 v[34:49], v[118:121], v[126:129], v[34:49]
	v_mfma_f32_32x32x16_bf16 v[2:17], v[122:125], v[126:129], v[2:17]
	s_waitcnt lgkmcnt(2)
	v_mfma_f32_32x32x16_bf16 v[50:65], v[118:121], v[142:145], v[50:65]
	ds_read_b128 v[118:121], v73 offset:96
	ds_read_b128 v[126:129], v73 offset:4704
	ds_read_b128 v[130:133], v74 offset:18528
	ds_read_b128 v[134:137], v74 offset:23136
	s_waitcnt vmcnt(9)
	ds_write_b128 v75, v[82:85] offset:46080
	s_waitcnt vmcnt(8)
	ds_write_b128 v75, v[110:113] offset:64512
	v_mfma_f32_32x32x16_bf16 v[18:33], v[122:125], v[142:145], v[18:33]
	global_load_dwordx4 v[82:85], v77, s[2:3] offset:1792
	global_load_dwordx4 v[110:113], v77, s[4:5] offset:1792
	s_waitcnt lgkmcnt(3)
	v_mfma_f32_32x32x16_bf16 v[34:49], v[118:121], v[130:133], v[34:49]
	s_waitcnt vmcnt(9)
	ds_write_b128 v75, v[86:89] offset:50688
	s_waitcnt vmcnt(8)
	ds_write_b128 v76, v[114:117] offset:13824
	v_mfma_f32_32x32x16_bf16 v[2:17], v[126:129], v[130:133], v[2:17]
	s_waitcnt lgkmcnt(4)
	v_mfma_f32_32x32x16_bf16 v[50:65], v[118:121], v[134:137], v[50:65]
	v_mfma_f32_32x32x16_bf16 v[18:33], v[126:129], v[134:137], v[18:33]
	s_waitcnt lgkmcnt(0)
	s_barrier
; #define GL1_(RA, RB, i) { RA[i] = *(const u32x4*)(ap + (aoff + (i) * astep)); if ((i) < NB) RB[(i) < NB ? (i) : 0] = *(const u32x4*)(bp + (boff + (i) * bstep)); }
; #define LS1_(RA, RB, ST, i) { char* sn_ = lds + (ST) * STAGE; *(u32x4*)(sn_ + wofs + (i) * 32 * LROW) = RA[i]; \
;                               if ((i) < NB) *(u32x4*)(sn_ + STAGE_OP + wofs + (i) * 32 * LROW) = RB[(i) < NB ? (i) : 0]; }
; template <int NJ> DI void gemm_mainloop_reg(const bf16_t* __restrict__ A, int lda, const bf16_t* __restrict__ Bt, int ldb, int K, f32x16 (&acc)[2][NJ], char* lds) {
;     ...
; #pragma unroll
;   for (int i = 0; i < 4; ++i) GL1_(ra0, rb0, i);
;   ap += 128; bp += 128;
; #pragma unroll
;   for (int i = 0; i < 4; ++i) GL1_(ra1, rb1, i);
;   ap += 128; bp += 128;
; #pragma unroll
;   for (int i = 0; i < 4; ++i) LS1_(ra0, rb0, 0, i);
;   __syncthreads();
;   const int nk = K >> 6;
;   for (int kt = 0; kt < nk; kt += 2) {
;     const bool l0 = (kt + 2 < nk), l1 = (kt + 3 < nk);
;     STEP_(0, l0, ra0, rb0, true, ra1, rb1);
;     __syncthreads();
;     STEP_(1, l1, ra1, rb1, l0, ra0, rb0);
;     __syncthreads();
	ds_read_b128 v[86:89], v73 offset:36864
	ds_read_b128 v[114:117], v74 offset:55296
	ds_read_b128 v[118:121], v73 offset:41472
	s_waitcnt lgkmcnt(1)
	v_mfma_f32_32x32x16_bf16 v[34:49], v[86:89], v[114:117], v[34:49]
	s_waitcnt lgkmcnt(0)
	v_mfma_f32_32x32x16_bf16 v[2:17], v[118:121], v[114:117], v[2:17]
	ds_read_b128 v[114:117], v74 offset:59904
	s_waitcnt lgkmcnt(0)
	v_mfma_f32_32x32x16_bf16 v[50:65], v[86:89], v[114:117], v[50:65]
	global_load_dwordx4 v[86:89], v80, s[2:3] offset:1920
	global_load_dwordx4 v[122:125], v80, s[4:5] offset:1920
	ds_read_b128 v[126:129], v73 offset:36896
	ds_read_b128 v[130:133], v74 offset:55328
	ds_read_b128 v[134:137], v73 offset:41504
	ds_read_b128 v[142:145], v74 offset:59936
	s_waitcnt vmcnt(9)
	ds_write_b128 v75, v[90:93]
	s_waitcnt vmcnt(8)
	ds_write_b128 v75, v[138:141] offset:18432
	v_mfma_f32_32x32x16_bf16 v[18:33], v[118:121], v[114:117], v[18:33]
	global_load_dwordx4 v[90:93], v79, s[2:3] offset:1920
	global_load_dwordx4 v[114:117], v79, s[4:5] offset:1920
	s_waitcnt lgkmcnt(4)
	v_mfma_f32_32x32x16_bf16 v[34:49], v[126:129], v[130:133], v[34:49]
	s_waitcnt lgkmcnt(3)
	v_mfma_f32_32x32x16_bf16 v[2:17], v[134:137], v[130:133], v[2:17]
	s_waitcnt lgkmcnt(2)
	v_mfma_f32_32x32x16_bf16 v[50:65], v[126:129], v[142:145], v[50:65]
	ds_read_b128 v[118:121], v73 offset:36928
	ds_read_b128 v[126:129], v73 offset:41536
	ds_read_b128 v[130:133], v74 offset:55360
	ds_read_b128 v[138:141], v74 offset:59968
	s_waitcnt vmcnt(9)
	ds_write_b128 v75, v[94:97] offset:4608
	s_waitcnt vmcnt(8)
	ds_write_b128 v75, v[98:101] offset:23040
	v_mfma_f32_32x32x16_bf16 v[18:33], v[134:137], v[142:145], v[18:33]
	global_load_dwordx4 v[94:97], v78, s[2:3] offset:1920
	s_nop 0
	global_load_dwordx4 v[78:81], v78, s[4:5] offset:1920
	s_waitcnt lgkmcnt(3)
	v_mfma_f32_32x32x16_bf16 v[34:49], v[118:121], v[130:133], v[34:49]
	v_mfma_f32_32x32x16_bf16 v[2:17], v[126:129], v[130:133], v[2:17]
	s_waitcnt lgkmcnt(2)
	v_mfma_f32_32x32x16_bf16 v[50:65], v[118:121], v[138:141], v[50:65]
	ds_read_b128 v[98:101], v73 offset:36960
	ds_read_b128 v[118:121], v73 offset:41568
	ds_read_b128 v[130:133], v74 offset:55392
	ds_read_b128 v[134:137], v74 offset:60000
	s_waitcnt vmcnt(9)
	ds_write_b128 v75, v[102:105] offset:9216
	s_waitcnt vmcnt(8)
	ds_write_b128 v75, v[106:109] offset:27648
	v_mfma_f32_32x32x16_bf16 v[18:33], v[126:129], v[138:141], v[18:33]
	s_waitcnt lgkmcnt(3)
	v_mfma_f32_32x32x16_bf16 v[34:49], v[98:101], v[130:133], v[34:49]
	s_waitcnt lgkmcnt(2)
	v_mfma_f32_32x32x16_bf16 v[50:65], v[98:101], v[134:137], v[50:65]
	global_load_dwordx4 v[98:101], v77, s[2:3] offset:1920
	global_load_dwordx4 v[102:105], v77, s[4:5] offset:1920
	s_waitcnt vmcnt(9)
	ds_write_b128 v75, v[82:85] offset:13824
	s_waitcnt vmcnt(8)
	ds_write_b128 v75, v[110:113] offset:32256
	v_mfma_f32_32x32x16_bf16 v[2:17], v[118:121], v[130:133], v[2:17]
	v_mfma_f32_32x32x16_bf16 v[18:33], v[118:121], v[134:137], v[18:33]
	s_waitcnt lgkmcnt(0)
	s_barrier
	ds_read_b128 v[82:85], v73
	ds_read_b128 v[106:109], v74 offset:18432
	ds_read_b128 v[110:113], v73 offset:4608
	s_waitcnt lgkmcnt(1)
	v_mfma_f32_32x32x16_bf16 v[34:49], v[82:85], v[106:109], v[34:49]
	s_waitcnt lgkmcnt(0)
	v_mfma_f32_32x32x16_bf16 v[2:17], v[110:113], v[106:109], v[2:17]
	ds_read_b128 v[106:109], v74 offset:23040
	s_waitcnt lgkmcnt(0)
	v_mfma_f32_32x32x16_bf16 v[50:65], v[82:85], v[106:109], v[50:65]
	ds_read_b128 v[82:85], v73 offset:32
	ds_read_b128 v[118:121], v74 offset:18464
	ds_read_b128 v[126:129], v73 offset:4640
	ds_read_b128 v[130:133], v74 offset:23072
	s_waitcnt vmcnt(7)
	ds_write_b128 v75, v[86:89] offset:36864
	s_waitcnt vmcnt(6)
	ds_write_b128 v75, v[122:125] offset:55296
	v_mfma_f32_32x32x16_bf16 v[18:33], v[110:113], v[106:109], v[18:33]
	s_waitcnt lgkmcnt(4)
	v_mfma_f32_32x32x16_bf16 v[34:49], v[82:85], v[118:121], v[34:49]
	s_waitcnt lgkmcnt(2)
	v_mfma_f32_32x32x16_bf16 v[50:65], v[82:85], v[130:133], v[50:65]
	ds_read_b128 v[82:85], v73 offset:64
	ds_read_b128 v[86:89], v73 offset:4672
	ds_read_b128 v[106:109], v74 offset:18496
	ds_read_b128 v[110:113], v74 offset:23104
	s_waitcnt vmcnt(5)
	ds_write_b128 v75, v[90:93] offset:41472
	s_waitcnt vmcnt(4)
	ds_write_b128 v75, v[114:117] offset:59904
	v_mfma_f32_32x32x16_bf16 v[2:17], v[126:129], v[118:121], v[2:17]
	v_mfma_f32_32x32x16_bf16 v[18:33], v[126:129], v[130:133], v[18:33]
	s_waitcnt lgkmcnt(3)
	v_mfma_f32_32x32x16_bf16 v[34:49], v[82:85], v[106:109], v[34:49]
	v_mfma_f32_32x32x16_bf16 v[2:17], v[86:89], v[106:109], v[2:17]
	s_waitcnt lgkmcnt(2)
	v_mfma_f32_32x32x16_bf16 v[50:65], v[82:85], v[110:113], v[50:65]
	ds_read_b128 v[82:85], v73 offset:96
	ds_read_b128 v[90:93], v73 offset:4704
	ds_read_b128 v[106:109], v74 offset:18528
	ds_read_b128 v[114:117], v74 offset:23136
	s_waitcnt vmcnt(3)
	ds_write_b128 v75, v[94:97] offset:46080
	s_waitcnt vmcnt(2)
	ds_write_b128 v75, v[78:81] offset:64512
	v_mfma_f32_32x32x16_bf16 v[18:33], v[86:89], v[110:113], v[18:33]
	s_waitcnt lgkmcnt(3)
	v_mfma_f32_32x32x16_bf16 v[34:49], v[82:85], v[106:109], v[34:49]
	s_waitcnt vmcnt(1)
	ds_write_b128 v75, v[98:101] offset:50688
	s_waitcnt vmcnt(0)
	ds_write_b128 v76, v[102:105] offset:13824
	v_mfma_f32_32x32x16_bf16 v[2:17], v[90:93], v[106:109], v[2:17]
	s_waitcnt lgkmcnt(4)
	v_mfma_f32_32x32x16_bf16 v[50:65], v[82:85], v[114:117], v[50:65]
	v_mfma_f32_32x32x16_bf16 v[18:33], v[90:93], v[114:117], v[18:33]
	s_waitcnt lgkmcnt(0)
	s_barrier
; DI int tid_() { int t = threadIdx.x; asm volatile("" : "+v"(t)); return t; }
; #define GL1_(RA, RB, i) { RA[i] = *(const u32x4*)(ap + (aoff + (i) * astep)); if ((i) < NB) RB[(i) < NB ? (i) : 0] = *(const u32x4*)(bp + (boff + (i) * bstep)); }
; #define LS1_(RA, RB, ST, i) { char* sn_ = lds + (ST) * STAGE; *(u32x4*)(sn_ + wofs + (i) * 32 * LROW) = RA[i]; \
;                               if ((i) < NB) *(u32x4*)(sn_ + STAGE_OP + wofs + (i) * 32 * LROW) = RB[(i) < NB ? (i) : 0]; }
; template <int NJ> DI void gemm_mainloop_reg(const bf16_t* __restrict__ A, int lda, const bf16_t* __restrict__ Bt, int ldb, int K, f32x16 (&acc)[2][NJ], char* lds) {
;     ...
; #pragma unroll
;   for (int i = 0; i < 4; ++i) GL1_(ra0, rb0, i);
;   ap += 128; bp += 128;
; #pragma unroll
;   for (int i = 0; i < 4; ++i) GL1_(ra1, rb1, i);
;   ap += 128; bp += 128;
; #pragma unroll
;   for (int i = 0; i < 4; ++i) LS1_(ra0, rb0, 0, i);
;   __syncthreads();
;   const int nk = K >> 6;
;   for (int kt = 0; kt < nk; kt += 2) {
;     const bool l0 = (kt + 2 < nk), l1 = (kt + 3 < nk);
;     STEP_(0, l0, ra0, rb0, true, ra1, rb1);
;     __syncthreads();
;     STEP_(1, l1, ra1, rb1, l0, ra0, rb0);
;     __syncthreads();
;   }
;     ...
; }
; template <int NJ> DI void acc_to_lds(const f32x16 (&acc)[2][NJ], float* cl) {
;   const int tid = tid_(), lane = tid & 63, w = tid >> 6, wm = w >> 1, wn = w & 1, h = lane >> 5, c = lane & 31;
; #pragma unroll
;   for (int i = 0; i < 2; ++i)
; #pragma unroll
;     for (int j = 0; j < NJ; ++j)
; #pragma unroll
;       for (int r = 0; r < 16; ++r) {
;         const int row = wm * 64 + i * 32 + (r & 3) + 8 * (r >> 2) + 4 * h;
;         cl[row * CLD + wn * 32 * NJ + j * 32 + c] = acc[i][j][r];
;       }
; DI void phase_ffn_in(const Ctx& c, const bf16_t* A, size_t woff, int site) {
;     ...
;     if (tid < 128) rr[tid] = rsqrtf(ss[mt * 128 + tid] * (1.0f / DM) + EPS);
;     __syncthreads();
	ds_read_b128 v[76:79], v73 offset:36864
	ds_read_b128 v[80:83], v74 offset:55296
	ds_read_b128 v[84:87], v73 offset:41472
	s_waitcnt lgkmcnt(1)
	v_mfma_f32_32x32x16_bf16 v[34:49], v[76:79], v[80:83], v[34:49]
	s_waitcnt lgkmcnt(0)
	v_mfma_f32_32x32x16_bf16 v[2:17], v[84:87], v[80:83], v[2:17]
	ds_read_b128 v[80:83], v74 offset:59904
	s_waitcnt lgkmcnt(0)
	v_mfma_f32_32x32x16_bf16 v[50:65], v[76:79], v[80:83], v[50:65]
	ds_read_b128 v[76:79], v73 offset:36896
	ds_read_b128 v[88:91], v74 offset:55328
	ds_read_b128 v[92:95], v73 offset:41504
	ds_read_b128 v[96:99], v74 offset:59936
	v_mfma_f32_32x32x16_bf16 v[18:33], v[84:87], v[80:83], v[18:33]
	s_waitcnt lgkmcnt(2)
	v_mfma_f32_32x32x16_bf16 v[34:49], v[76:79], v[88:91], v[34:49]
	s_waitcnt lgkmcnt(1)
	v_mfma_f32_32x32x16_bf16 v[2:17], v[92:95], v[88:91], v[2:17]
	s_waitcnt lgkmcnt(0)
	v_mfma_f32_32x32x16_bf16 v[50:65], v[76:79], v[96:99], v[50:65]
	ds_read_b128 v[76:79], v73 offset:36928
	ds_read_b128 v[80:83], v73 offset:41536
	ds_read_b128 v[84:87], v74 offset:55360
	ds_read_b128 v[88:91], v74 offset:59968
	v_mfma_f32_32x32x16_bf16 v[18:33], v[92:95], v[96:99], v[18:33]
	s_waitcnt lgkmcnt(1)
	v_mfma_f32_32x32x16_bf16 v[34:49], v[76:79], v[84:87], v[34:49]
	v_mfma_f32_32x32x16_bf16 v[2:17], v[80:83], v[84:87], v[2:17]
	s_waitcnt lgkmcnt(0)
	v_mfma_f32_32x32x16_bf16 v[50:65], v[76:79], v[88:91], v[50:65]
	ds_read_b128 v[76:79], v73 offset:36960
	ds_read_b128 v[84:87], v73 offset:41568
	ds_read_b128 v[92:95], v74 offset:55392
	ds_read_b128 v[96:99], v74 offset:60000
	v_mfma_f32_32x32x16_bf16 v[18:33], v[80:83], v[88:91], v[18:33]
	s_waitcnt lgkmcnt(1)
	v_mfma_f32_32x32x16_bf16 v[34:49], v[76:79], v[92:95], v[34:49]
	v_mfma_f32_32x32x16_bf16 v[2:17], v[84:87], v[92:95], v[2:17]
	s_waitcnt lgkmcnt(0)
	v_mfma_f32_32x32x16_bf16 v[50:65], v[76:79], v[96:99], v[50:65]
	v_mfma_f32_32x32x16_bf16 v[18:33], v[84:87], v[96:99], v[18:33]
	s_setprio 0
	s_nop 0
	v_mov_b32_e32 v73, v199
	s_barrier
	s_nop 0
	v_lshrrev_b32_e32 v75, 3, v73
	v_lshrrev_b32_e32 v74, 1, v73
	v_and_b32_e32 v75, 4, v75
	v_and_b32_e32 v73, 0x5f, v73
	v_and_or_b32 v74, v74, s17, v75
	v_mul_lo_u32 v74, v74, s15
	v_lshlrev_b32_e32 v73, 2, v73
	v_add3_u32 v73, 0, v74, v73
	ds_write2_b32 v73, v34, v50 offset1:32
	ds_write2_b32 v73, v35, v51 offset0:132 offset1:164
	v_add_u32_e32 v34, 0x400, v73
	ds_write2_b32 v34, v36, v52 offset0:8 offset1:40
	ds_write2_b32 v34, v37, v53 offset0:140 offset1:172
	v_add_u32_e32 v34, 0x1000, v73
	ds_write2_b32 v34, v38, v54 offset0:32 offset1:64
	ds_write2_b32 v34, v39, v55 offset0:164 offset1:196
	v_add_u32_e32 v34, 0x1400, v73
	ds_write2_b32 v34, v40, v56 offset0:40 offset1:72
	ds_write2_b32 v34, v41, v57 offset0:172 offset1:204
	v_add_u32_e32 v34, 0x2000, v73
	ds_write2_b32 v34, v42, v58 offset0:64 offset1:96
	ds_write2_b32 v34, v43, v59 offset0:196 offset1:228
	v_add_u32_e32 v34, 0x2400, v73
	ds_write2_b32 v34, v44, v60 offset0:72 offset1:104
	ds_write2_b32 v34, v45, v61 offset0:204 offset1:236
	v_add_u32_e32 v34, 0x3000, v73
	ds_write2_b32 v34, v46, v62 offset0:96 offset1:128
	v_add_u32_e32 v34, 0x3200, v73
	ds_write2_b32 v34, v47, v63 offset0:100 offset1:132
	v_add_u32_e32 v34, 0x3400, v73
	ds_write2_b32 v34, v48, v64 offset0:104 offset1:136
	v_add_u32_e32 v34, 0x3600, v73
	ds_write2_b32 v34, v49, v65 offset0:108 offset1:140
	v_add_u32_e32 v34, 0x4000, v73
	ds_write2_b32 v34, v2, v18 offset0:128 offset1:160
	v_add_u32_e32 v2, 0x4400, v73
	ds_write2_b32 v2, v3, v19 offset0:4 offset1:36
	ds_write2_b32 v2, v4, v20 offset0:136 offset1:168
	v_add_u32_e32 v2, 0x4800, v73
	ds_write2_b32 v2, v5, v21 offset0:12 offset1:44
	v_add_u32_e32 v2, 0x5000, v73
	ds_write2_b32 v2, v6, v22 offset0:160 offset1:192
	v_add_u32_e32 v2, 0x5400, v73
	ds_write2_b32 v2, v7, v23 offset0:36 offset1:68
	ds_write2_b32 v2, v8, v24 offset0:168 offset1:200
	v_add_u32_e32 v2, 0x5800, v73
	ds_write2_b32 v2, v9, v25 offset0:44 offset1:76
	v_add_u32_e32 v2, 0x6000, v73
	ds_write2_b32 v2, v10, v26 offset0:192 offset1:224
	v_add_u32_e32 v2, 0x6400, v73
	ds_write2_b32 v2, v11, v27 offset0:68 offset1:100
	ds_write2_b32 v2, v12, v28 offset0:200 offset1:232
	v_add_u32_e32 v2, 0x6800, v73
	ds_write2_b32 v2, v13, v29 offset0:76 offset1:108
	v_add_u32_e32 v2, 0x7200, v73
	ds_write2_b32 v2, v14, v30 offset0:96 offset1:128
	v_add_u32_e32 v2, 0x7400, v73
	ds_write2_b32 v2, v15, v31 offset0:100 offset1:132
	v_add_u32_e32 v2, 0x7600, v73
	ds_write2_b32 v2, v16, v32 offset0:104 offset1:136
	v_add_u32_e32 v2, 0x7800, v73
	ds_write2_b32 v2, v17, v33 offset0:108 offset1:140
	s_and_saveexec_b64 s[2:3], s[36:37]
	s_cbranch_execz .LBB0_369
	v_lshl_add_u32 v2, s34, 7, v68
	v_readlane_b32 s4, v248, 14
	v_ashrrev_i32_e32 v3, 31, v2
	v_readlane_b32 s5, v248, 15
	s_nop 1
	v_lshl_add_u64 v[2:3], v[2:3], 2, s[4:5]
	v_mov_b32_e32 v2, v253
	s_nop 0
	s_mov_b32 s4, 0x800000
	s_waitcnt vmcnt(0)
	v_fmamk_f32 v2, v2, 0x3a800000, v198
	v_mul_f32_e32 v3, 0x4b800000, v2
	v_cmp_gt_f32_e32 vcc, s4, v2
	s_nop 1
	v_cndmask_b32_e32 v2, v2, v3, vcc
	v_rsq_f32_e32 v2, v2
	s_nop 0
	v_mul_f32_e32 v3, 0x45800000, v2
	v_cndmask_b32_e32 v2, v2, v3, vcc
	ds_write_b32 v69, v2

; DI int tid_() { int t = threadIdx.x; asm volatile("" : "+v"(t)); return t; }
; #define GL1_(RA, RB, i) { RA[i] = *(const u32x4*)(ap + (aoff + (i) * astep)); if ((i) < NB) RB[(i) < NB ? (i) : 0] = *(const u32x4*)(bp + (boff + (i) * bstep)); }
; #define LS1_(RA, RB, ST, i) { char* sn_ = lds + (ST) * STAGE; *(u32x4*)(sn_ + wofs + (i) * 32 * LROW) = RA[i]; \
;                               if ((i) < NB) *(u32x4*)(sn_ + STAGE_OP + wofs + (i) * 32 * LROW) = RB[(i) < NB ? (i) : 0]; }
; template <int NJ> DI void gemm_mainloop_reg(const bf16_t* __restrict__ A, int lda, const bf16_t* __restrict__ Bt, int ldb, int K, f32x16 (&acc)[2][NJ], char* lds) {
;   const int tid = tid_(), lane = tid & 63, w = tid >> 6, wm = w >> 1, wn = w & 1;
;   const int lr = tid >> 3, lc = tid & 7;
;   const char* ap = (const char*)A;
;   const char* bp = (const char*)Bt;
;   const unsigned aoff = (unsigned)(lr * lda + lc * 8) * 2u, boff = (unsigned)(lr * ldb + lc * 8) * 2u;
;   const unsigned astep = (unsigned)(32 * lda) * 2u, bstep = (unsigned)(32 * ldb) * 2u;
;   constexpr int NB = 2 * NJ;
;   u32x4 ra0[4], rb0[NB], ra1[4], rb1[NB];
;   const int wofs = lr * LROW + lc * 16;
;   const int a_rd = (wm * 64 + (lane & 31)) * LROW + (lane >> 5) * 16;
;   const int b_rd = STAGE_OP + (wn * 32 * NJ + (lane & 31)) * LROW + (lane >> 5) * 16;
;     ...
; #pragma unroll
;   for (int i = 0; i < 4; ++i) GL1_(ra0, rb0, i);
;   ap += 128; bp += 128;
; #pragma unroll
;   for (int i = 0; i < 4; ++i) GL1_(ra1, rb1, i);
;   ap += 128; bp += 128;
; #pragma unroll
;   for (int i = 0; i < 4; ++i) LS1_(ra0, rb0, 0, i);
;   __syncthreads();
; DI void phase_ffn_in(const Ctx& c, const bf16_t* A, size_t woff, int site) {
;     ...
;   for (;;) {
;     const int j_ = grab_next(ctr, c.lds);
;     if (j_ >= 128 * 6) break;
;     const int mt = xcd_ * 16 + (j_ & 7) + 8 * ((j_ >> 6) & 1), nt = (j_ >> 7) * 8 + ((j_ >> 3) & 7);
;     if (nt >= 44) continue;
;     f32x16 acc[2][2]; zero_acc<2>(acc);
;     gemm_mainloop_reg<2>(A + (size_t)mt * 128 * LDX, LDX, Bt + (size_t)nt * 128 * LDX, LDX, DM, acc, c.lds);
;     acc_to_lds<2>(acc, cl);
;     if (tid < 128) rr[tid] = rsqrtf(ss[mt * 128 + tid] * (1.0f / DM) + EPS);
.LBB0_1094:
	s_or_b64 exec, exec, s[2:3]
	s_cmp_lg_u32 s24, -1
	s_cselect_b32 s2, s24, 0
	s_cselect_b32 s3, s79, 0
	v_mov_b32_e32 v2, s2
	v_mov_b32_e32 v3, s3
	s_waitcnt lgkmcnt(0)
	s_barrier
	flat_load_dword v2, v[2:3] sc0 sc1
	s_waitcnt vmcnt(0)
	s_mov_b64 s[2:3], -1
	s_waitcnt lgkmcnt(0)
	s_barrier
	v_readfirstlane_b32 s4, v2
	s_cmpk_gt_i32 s4, 0x2ff
	s_cbranch_scc1 .LBB0_1089
	s_ashr_i32 s2, s4, 4
	s_and_b32 s2, s2, -8
	s_bfe_u32 s3, s4, 0x30003
	s_or_b32 s6, s2, s3
	s_cmp_gt_i32 s6, 43
	s_cbranch_scc1 .LBB0_1088
	s_lshr_b32 s2, s4, 3
	s_and_b32 s7, s4, 7
	s_and_b32 s27, s2, 8
	s_or_b32 s2, s7, s27
	v_readlane_b32 s3, v250, 20
	s_or_b32 s36, s2, s3
	v_and_b32_e32 v254, 0x7f, v68
	v_lshl_add_u32 v254, s36, 7, v254
	v_ashrrev_i32_e32 v255, 31, v254
	v_lshl_add_u64 v[254:255], v[254:255], 2, s[0:1]
	global_load_dword v253, v[254:255], off
	s_nop 0
	v_mov_b32_e32 v34, v199
	s_mul_i32 s2, s36, 0x44000
	v_readlane_b32 s3, v252, 10
	s_add_u32 s2, s3, s2
	v_ashrrev_i32_e32 v35, 3, v34
	v_lshlrev_b32_e32 v2, 4, v34
	v_readlane_b32 s3, v252, 11
	v_and_b32_e32 v36, 0x70, v2
	v_mul_lo_u32 v2, v35, s9
	s_addc_u32 s3, s3, 0
	s_mul_i32 s4, s6, 0x44000
	v_or_b32_e32 v80, v36, v2
	s_mul_hi_i32 s5, s6, 0x44000
	s_add_u32 s4, s25, s4
	v_add_u32_e32 v79, 0x11000, v80
	v_add_u32_e32 v78, 0x22000, v80
	v_add_u32_e32 v77, 0x33000, v80
	s_addc_u32 s5, s26, s5
	global_load_dwordx4 v[2:5], v80, s[2:3]
	global_load_dwordx4 v[6:9], v79, s[2:3]
	global_load_dwordx4 v[10:13], v78, s[2:3]
	global_load_dwordx4 v[14:17], v77, s[2:3]
	global_load_dwordx4 v[18:21], v80, s[4:5]
	global_load_dwordx4 v[22:25], v79, s[4:5]
	global_load_dwordx4 v[26:29], v78, s[4:5]
	global_load_dwordx4 v[30:33], v77, s[4:5]
	v_mul_lo_u32 v35, v35, s16
	v_lshrrev_b32_e32 v37, 1, v34
	v_and_b32_e32 v38, 31, v34
	v_add3_u32 v75, v35, v36, 0
	v_and_b32_e32 v39, 16, v37
	v_and_or_b32 v37, v37, s17, v38
	global_load_dwordx4 v[82:85], v80, s[2:3] offset:128
	global_load_dwordx4 v[86:89], v79, s[2:3] offset:128
	global_load_dwordx4 v[90:93], v78, s[2:3] offset:128
	global_load_dwordx4 v[94:97], v77, s[2:3] offset:128
	global_load_dwordx4 v[98:101], v80, s[4:5] offset:128
	global_load_dwordx4 v[102:105], v79, s[4:5] offset:128
	global_load_dwordx4 v[106:109], v78, s[4:5] offset:128
	global_load_dwordx4 v[110:113], v77, s[4:5] offset:128
	v_mul_lo_u32 v35, v37, s16
	v_add3_u32 v73, v35, v39, 0
	v_add_u32_e32 v76, 0xd800, v75
	s_waitcnt vmcnt(15)
	ds_write_b128 v75, v[2:5]
	s_waitcnt vmcnt(14)
	ds_write_b128 v75, v[6:9] offset:4608
	s_waitcnt vmcnt(13)
	ds_write_b128 v75, v[10:13] offset:9216
	s_waitcnt vmcnt(12)
	ds_write_b128 v75, v[14:17] offset:13824
	s_waitcnt vmcnt(11)
	ds_write_b128 v75, v[18:21] offset:18432
	s_waitcnt vmcnt(10)
	ds_write_b128 v75, v[22:25] offset:23040
	s_waitcnt vmcnt(9)
	ds_write_b128 v75, v[26:29] offset:27648
	s_waitcnt vmcnt(8)
	ds_write_b128 v75, v[30:33] offset:32256
	v_and_b32_e32 v2, 0x5f, v34
	v_mul_u32_u24_e32 v2, 0x90, v2
	v_add3_u32 v74, v2, v39, 0
	s_waitcnt lgkmcnt(0)
	s_barrier
	ds_read_b128 v[18:21], v73
	ds_read_b128 v[2:5], v74 offset:18432
	ds_read_b128 v[114:117], v73 offset:32
	ds_read_b128 v[118:121], v74 offset:18464
	ds_read_b128 v[22:25], v73 offset:4608
	ds_read_b128 v[122:125], v73 offset:4640
	ds_read_b128 v[26:29], v74 offset:23040
	ds_read_b128 v[126:129], v74 offset:23072
	global_load_dwordx4 v[130:133], v80, s[2:3] offset:256
	global_load_dwordx4 v[134:137], v80, s[4:5] offset:256
	s_waitcnt lgkmcnt(6)
	s_setprio 1
	s_nop 0
	v_mfma_f32_32x32x16_bf16 v[34:49], v[18:21], v[2:5], 0
	s_waitcnt vmcnt(9)
	ds_write_b128 v75, v[82:85] offset:36864
	s_waitcnt vmcnt(5)
	ds_write_b128 v75, v[98:101] offset:55296
	s_waitcnt lgkmcnt(5)
	v_mfma_f32_32x32x16_bf16 v[2:17], v[22:25], v[2:5], 0
	s_waitcnt lgkmcnt(3)
	v_mfma_f32_32x32x16_bf16 v[50:65], v[18:21], v[26:29], 0
	v_mfma_f32_32x32x16_bf16 v[18:33], v[22:25], v[26:29], 0
	global_load_dwordx4 v[82:85], v79, s[2:3] offset:256
	global_load_dwordx4 v[98:101], v79, s[4:5] offset:256
	v_mfma_f32_32x32x16_bf16 v[34:49], v[114:117], v[118:121], v[34:49]
	v_mfma_f32_32x32x16_bf16 v[2:17], v[122:125], v[118:121], v[2:17]
	s_waitcnt lgkmcnt(2)
	v_mfma_f32_32x32x16_bf16 v[50:65], v[114:117], v[126:129], v[50:65]
	ds_read_b128 v[114:117], v73 offset:64
	ds_read_b128 v[118:121], v73 offset:4672
	ds_read_b128 v[138:141], v74 offset:18496
	ds_read_b128 v[142:145], v74 offset:23104
	ds_write_b128 v75, v[86:89] offset:41472
	s_waitcnt vmcnt(6)
	ds_write_b128 v75, v[102:105] offset:59904
	v_mfma_f32_32x32x16_bf16 v[18:33], v[122:125], v[126:129], v[18:33]
	global_load_dwordx4 v[86:89], v78, s[2:3] offset:256
	global_load_dwordx4 v[102:105], v78, s[4:5] offset:256
	s_waitcnt lgkmcnt(3)
	v_mfma_f32_32x32x16_bf16 v[34:49], v[114:117], v[138:141], v[34:49]
	v_mfma_f32_32x32x16_bf16 v[2:17], v[118:121], v[138:141], v[2:17]
	s_waitcnt lgkmcnt(2)
	v_mfma_f32_32x32x16_bf16 v[50:65], v[114:117], v[142:145], v[50:65]
	ds_read_b128 v[114:117], v73 offset:96
	ds_read_b128 v[122:125], v73 offset:4704
	ds_read_b128 v[126:129], v74 offset:18528
	ds_read_b128 v[138:141], v74 offset:23136
	ds_write_b128 v75, v[90:93] offset:46080
	s_waitcnt vmcnt(7)
	ds_write_b128 v75, v[106:109] offset:64512
	v_mfma_f32_32x32x16_bf16 v[18:33], v[118:121], v[142:145], v[18:33]
	global_load_dwordx4 v[90:93], v77, s[2:3] offset:256
	global_load_dwordx4 v[106:109], v77, s[4:5] offset:256
	s_waitcnt lgkmcnt(3)
	v_mfma_f32_32x32x16_bf16 v[34:49], v[114:117], v[126:129], v[34:49]
	ds_write_b128 v75, v[94:97] offset:50688
	s_waitcnt vmcnt(8)
	ds_write_b128 v76, v[110:113] offset:13824
	v_mfma_f32_32x32x16_bf16 v[2:17], v[122:125], v[126:129], v[2:17]
	s_waitcnt lgkmcnt(4)
	v_mfma_f32_32x32x16_bf16 v[50:65], v[114:117], v[138:141], v[50:65]
	v_mfma_f32_32x32x16_bf16 v[18:33], v[122:125], v[138:141], v[18:33]
	s_waitcnt lgkmcnt(0)
	s_barrier
; #define GL1_(RA, RB, i) { RA[i] = *(const u32x4*)(ap + (aoff + (i) * astep)); if ((i) < NB) RB[(i) < NB ? (i) : 0] = *(const u32x4*)(bp + (boff + (i) * bstep)); }
; #define LS1_(RA, RB, ST, i) { char* sn_ = lds + (ST) * STAGE; *(u32x4*)(sn_ + wofs + (i) * 32 * LROW) = RA[i]; \
;                               if ((i) < NB) *(u32x4*)(sn_ + STAGE_OP + wofs + (i) * 32 * LROW) = RB[(i) < NB ? (i) : 0]; }
; template <int NJ> DI void gemm_mainloop_reg(const bf16_t* __restrict__ A, int lda, const bf16_t* __restrict__ Bt, int ldb, int K, f32x16 (&acc)[2][NJ], char* lds) {
;     ...
; #pragma unroll
;   for (int i = 0; i < 4; ++i) GL1_(ra0, rb0, i);
;   ap += 128; bp += 128;
; #pragma unroll
;   for (int i = 0; i < 4; ++i) GL1_(ra1, rb1, i);
;   ap += 128; bp += 128;
; #pragma unroll
;   for (int i = 0; i < 4; ++i) LS1_(ra0, rb0, 0, i);
;   __syncthreads();
;   const int nk = K >> 6;
;   for (int kt = 0; kt < nk; kt += 2) {
;     const bool l0 = (kt + 2 < nk), l1 = (kt + 3 < nk);
;     STEP_(0, l0, ra0, rb0, true, ra1, rb1);
;     __syncthreads();
;     STEP_(1, l1, ra1, rb1, l0, ra0, rb0);
;     __syncthreads();
;   }
	ds_read_b128 v[94:97], v73 offset:36864
	ds_read_b128 v[110:113], v74 offset:55296
	ds_read_b128 v[114:117], v73 offset:36896
	ds_read_b128 v[118:121], v74 offset:55328
	ds_read_b128 v[122:125], v73 offset:41472
	ds_read_b128 v[126:129], v73 offset:41504
	s_waitcnt lgkmcnt(4)
	v_mfma_f32_32x32x16_bf16 v[34:49], v[94:97], v[110:113], v[34:49]
	s_waitcnt lgkmcnt(1)
	v_mfma_f32_32x32x16_bf16 v[2:17], v[122:125], v[110:113], v[2:17]
	ds_read_b128 v[110:113], v74 offset:59904
	ds_read_b128 v[138:141], v74 offset:59936
	s_waitcnt lgkmcnt(1)
	v_mfma_f32_32x32x16_bf16 v[50:65], v[94:97], v[110:113], v[50:65]
	global_load_dwordx4 v[94:97], v80, s[2:3] offset:384
	global_load_dwordx4 v[142:145], v80, s[4:5] offset:384
	s_waitcnt vmcnt(9)
	ds_write_b128 v75, v[130:133]
	s_waitcnt vmcnt(8)
	ds_write_b128 v75, v[134:137] offset:18432
	v_mfma_f32_32x32x16_bf16 v[18:33], v[122:125], v[110:113], v[18:33]
	v_mfma_f32_32x32x16_bf16 v[34:49], v[114:117], v[118:121], v[34:49]
	s_waitcnt lgkmcnt(2)
	v_mfma_f32_32x32x16_bf16 v[50:65], v[114:117], v[138:141], v[50:65]
	global_load_dwordx4 v[110:113], v79, s[2:3] offset:384
	global_load_dwordx4 v[114:117], v79, s[4:5] offset:384
	v_mfma_f32_32x32x16_bf16 v[2:17], v[126:129], v[118:121], v[2:17]
	ds_read_b128 v[118:121], v73 offset:36928
	ds_read_b128 v[122:125], v73 offset:41536
	ds_read_b128 v[130:133], v74 offset:55360
	ds_read_b128 v[134:137], v74 offset:59968
	s_waitcnt vmcnt(9)
	ds_write_b128 v75, v[82:85] offset:4608
	s_waitcnt vmcnt(8)
	ds_write_b128 v75, v[98:101] offset:23040
	v_mfma_f32_32x32x16_bf16 v[18:33], v[126:129], v[138:141], v[18:33]
	global_load_dwordx4 v[82:85], v78, s[2:3] offset:384
	global_load_dwordx4 v[98:101], v78, s[4:5] offset:384
	s_waitcnt lgkmcnt(3)
	v_mfma_f32_32x32x16_bf16 v[34:49], v[118:121], v[130:133], v[34:49]
	v_mfma_f32_32x32x16_bf16 v[2:17], v[122:125], v[130:133], v[2:17]
	s_waitcnt lgkmcnt(2)
	v_mfma_f32_32x32x16_bf16 v[50:65], v[118:121], v[134:137], v[50:65]
	ds_read_b128 v[118:121], v73 offset:36960
	ds_read_b128 v[126:129], v73 offset:41568
	ds_read_b128 v[130:133], v74 offset:55392
	ds_read_b128 v[138:141], v74 offset:60000
	s_waitcnt vmcnt(9)
	ds_write_b128 v75, v[86:89] offset:9216
	s_waitcnt vmcnt(8)
	ds_write_b128 v75, v[102:105] offset:27648
	v_mfma_f32_32x32x16_bf16 v[18:33], v[122:125], v[134:137], v[18:33]
	global_load_dwordx4 v[86:89], v77, s[2:3] offset:384
	global_load_dwordx4 v[102:105], v77, s[4:5] offset:384
	s_waitcnt lgkmcnt(3)
	v_mfma_f32_32x32x16_bf16 v[34:49], v[118:121], v[130:133], v[34:49]
	s_waitcnt vmcnt(9)
	ds_write_b128 v75, v[90:93] offset:13824
	s_waitcnt vmcnt(8)
	ds_write_b128 v75, v[106:109] offset:32256
	v_mfma_f32_32x32x16_bf16 v[2:17], v[126:129], v[130:133], v[2:17]
	s_waitcnt lgkmcnt(4)
	v_mfma_f32_32x32x16_bf16 v[50:65], v[118:121], v[138:141], v[50:65]
	v_mfma_f32_32x32x16_bf16 v[18:33], v[126:129], v[138:141], v[18:33]
	s_waitcnt lgkmcnt(0)
	s_barrier
	ds_read_b128 v[90:93], v73
	ds_read_b128 v[106:109], v74 offset:18432
	ds_read_b128 v[118:121], v73 offset:32
	ds_read_b128 v[122:125], v74 offset:18464
	ds_read_b128 v[126:129], v73 offset:4608
	ds_read_b128 v[130:133], v73 offset:4640
	s_waitcnt lgkmcnt(4)
	v_mfma_f32_32x32x16_bf16 v[34:49], v[90:93], v[106:109], v[34:49]
	s_waitcnt lgkmcnt(1)
	v_mfma_f32_32x32x16_bf16 v[2:17], v[126:129], v[106:109], v[2:17]
	ds_read_b128 v[106:109], v74 offset:23040
	ds_read_b128 v[134:137], v74 offset:23072
	s_waitcnt lgkmcnt(1)
	v_mfma_f32_32x32x16_bf16 v[50:65], v[90:93], v[106:109], v[50:65]
	global_load_dwordx4 v[90:93], v80, s[2:3] offset:512
	global_load_dwordx4 v[138:141], v80, s[4:5] offset:512
	s_waitcnt vmcnt(9)
	ds_write_b128 v75, v[94:97] offset:36864
	s_waitcnt vmcnt(8)
	ds_write_b128 v75, v[142:145] offset:55296
	v_mfma_f32_32x32x16_bf16 v[18:33], v[126:129], v[106:109], v[18:33]
	global_load_dwordx4 v[94:97], v79, s[2:3] offset:512
	global_load_dwordx4 v[106:109], v79, s[4:5] offset:512
	v_mfma_f32_32x32x16_bf16 v[34:49], v[118:121], v[122:125], v[34:49]
	v_mfma_f32_32x32x16_bf16 v[2:17], v[130:133], v[122:125], v[2:17]
	s_waitcnt lgkmcnt(2)
	v_mfma_f32_32x32x16_bf16 v[50:65], v[118:121], v[134:137], v[50:65]
	ds_read_b128 v[118:121], v73 offset:64
	ds_read_b128 v[122:125], v73 offset:4672
	ds_read_b128 v[126:129], v74 offset:18496
	ds_read_b128 v[142:145], v74 offset:23104
	s_waitcnt vmcnt(9)
	ds_write_b128 v75, v[110:113] offset:41472
	s_waitcnt vmcnt(8)
	ds_write_b128 v75, v[114:117] offset:59904
	v_mfma_f32_32x32x16_bf16 v[18:33], v[130:133], v[134:137], v[18:33]
	global_load_dwordx4 v[110:113], v78, s[2:3] offset:512
	global_load_dwordx4 v[114:117], v78, s[4:5] offset:512
	s_waitcnt lgkmcnt(3)
	v_mfma_f32_32x32x16_bf16 v[34:49], v[118:121], v[126:129], v[34:49]
	v_mfma_f32_32x32x16_bf16 v[2:17], v[122:125], v[126:129], v[2:17]
	s_waitcnt lgkmcnt(2)
	v_mfma_f32_32x32x16_bf16 v[50:65], v[118:121], v[142:145], v[50:65]
	ds_read_b128 v[118:121], v73 offset:96
	ds_read_b128 v[126:129], v73 offset:4704
	ds_read_b128 v[130:133], v74 offset:18528
	ds_read_b128 v[134:137], v74 offset:23136
	s_waitcnt vmcnt(9)
	ds_write_b128 v75, v[82:85] offset:46080
	s_waitcnt vmcnt(8)
	ds_write_b128 v75, v[98:101] offset:64512
	v_mfma_f32_32x32x16_bf16 v[18:33], v[122:125], v[142:145], v[18:33]
	global_load_dwordx4 v[82:85], v77, s[2:3] offset:512
	global_load_dwordx4 v[98:101], v77, s[4:5] offset:512
	s_waitcnt lgkmcnt(3)
	v_mfma_f32_32x32x16_bf16 v[34:49], v[118:121], v[130:133], v[34:49]
	s_waitcnt vmcnt(9)
	ds_write_b128 v75, v[86:89] offset:50688
	s_waitcnt vmcnt(8)
	ds_write_b128 v76, v[102:105] offset:13824
	v_mfma_f32_32x32x16_bf16 v[2:17], v[126:129], v[130:133], v[2:17]
	s_waitcnt lgkmcnt(4)
	v_mfma_f32_32x32x16_bf16 v[50:65], v[118:121], v[134:137], v[50:65]
	v_mfma_f32_32x32x16_bf16 v[18:33], v[126:129], v[134:137], v[18:33]
	s_waitcnt lgkmcnt(0)
	s_barrier
; #define GL1_(RA, RB, i) { RA[i] = *(const u32x4*)(ap + (aoff + (i) * astep)); if ((i) < NB) RB[(i) < NB ? (i) : 0] = *(const u32x4*)(bp + (boff + (i) * bstep)); }
; #define LS1_(RA, RB, ST, i) { char* sn_ = lds + (ST) * STAGE; *(u32x4*)(sn_ + wofs + (i) * 32 * LROW) = RA[i]; \
;                               if ((i) < NB) *(u32x4*)(sn_ + STAGE_OP + wofs + (i) * 32 * LROW) = RB[(i) < NB ? (i) : 0]; }
; template <int NJ> DI void gemm_mainloop_reg(const bf16_t* __restrict__ A, int lda, const bf16_t* __restrict__ Bt, int ldb, int K, f32x16 (&acc)[2][NJ], char* lds) {
;     ...
; #pragma unroll
;   for (int i = 0; i < 4; ++i) GL1_(ra0, rb0, i);
;   ap += 128; bp += 128;
; #pragma unroll
;   for (int i = 0; i < 4; ++i) GL1_(ra1, rb1, i);
;   ap += 128; bp += 128;
; #pragma unroll
;   for (int i = 0; i < 4; ++i) LS1_(ra0, rb0, 0, i);
;   __syncthreads();
;   const int nk = K >> 6;
;   for (int kt = 0; kt < nk; kt += 2) {
;     const bool l0 = (kt + 2 < nk), l1 = (kt + 3 < nk);
;     STEP_(0, l0, ra0, rb0, true, ra1, rb1);
;     __syncthreads();
;     STEP_(1, l1, ra1, rb1, l0, ra0, rb0);
;     __syncthreads();
;   }
	ds_read_b128 v[86:89], v73 offset:36864
	ds_read_b128 v[102:105], v74 offset:55296
	ds_read_b128 v[118:121], v73 offset:36896
	ds_read_b128 v[122:125], v74 offset:55328
	ds_read_b128 v[126:129], v73 offset:41472
	ds_read_b128 v[130:133], v73 offset:41504
	s_waitcnt lgkmcnt(4)
	v_mfma_f32_32x32x16_bf16 v[34:49], v[86:89], v[102:105], v[34:49]
	s_waitcnt lgkmcnt(1)
	v_mfma_f32_32x32x16_bf16 v[2:17], v[126:129], v[102:105], v[2:17]
	ds_read_b128 v[102:105], v74 offset:59904
	ds_read_b128 v[134:137], v74 offset:59936
	s_waitcnt lgkmcnt(1)
	v_mfma_f32_32x32x16_bf16 v[50:65], v[86:89], v[102:105], v[50:65]
	global_load_dwordx4 v[86:89], v80, s[2:3] offset:640
	global_load_dwordx4 v[142:145], v80, s[4:5] offset:640
	s_waitcnt vmcnt(9)
	ds_write_b128 v75, v[90:93]
	s_waitcnt vmcnt(8)
	ds_write_b128 v75, v[138:141] offset:18432
	v_mfma_f32_32x32x16_bf16 v[18:33], v[126:129], v[102:105], v[18:33]
	global_load_dwordx4 v[90:93], v79, s[2:3] offset:640
	global_load_dwordx4 v[102:105], v79, s[4:5] offset:640
	v_mfma_f32_32x32x16_bf16 v[34:49], v[118:121], v[122:125], v[34:49]
	v_mfma_f32_32x32x16_bf16 v[2:17], v[130:133], v[122:125], v[2:17]
	s_waitcnt lgkmcnt(2)
	v_mfma_f32_32x32x16_bf16 v[50:65], v[118:121], v[134:137], v[50:65]
	ds_read_b128 v[118:121], v73 offset:36928
	ds_read_b128 v[122:125], v73 offset:41536
	ds_read_b128 v[126:129], v74 offset:55360
	ds_read_b128 v[138:141], v74 offset:59968
	s_waitcnt vmcnt(9)
	ds_write_b128 v75, v[94:97] offset:4608
	s_waitcnt vmcnt(8)
	ds_write_b128 v75, v[106:109] offset:23040
	v_mfma_f32_32x32x16_bf16 v[18:33], v[130:133], v[134:137], v[18:33]
	global_load_dwordx4 v[94:97], v78, s[2:3] offset:640
	global_load_dwordx4 v[106:109], v78, s[4:5] offset:640
	s_waitcnt lgkmcnt(3)
	v_mfma_f32_32x32x16_bf16 v[34:49], v[118:121], v[126:129], v[34:49]
	v_mfma_f32_32x32x16_bf16 v[2:17], v[122:125], v[126:129], v[2:17]
	s_waitcnt lgkmcnt(2)
	v_mfma_f32_32x32x16_bf16 v[50:65], v[118:121], v[138:141], v[50:65]
	ds_read_b128 v[118:121], v73 offset:36960
	ds_read_b128 v[126:129], v73 offset:41568
	ds_read_b128 v[130:133], v74 offset:55392
	ds_read_b128 v[134:137], v74 offset:60000
	s_waitcnt vmcnt(9)
	ds_write_b128 v75, v[110:113] offset:9216
	s_waitcnt vmcnt(8)
	ds_write_b128 v75, v[114:117] offset:27648
	v_mfma_f32_32x32x16_bf16 v[18:33], v[122:125], v[138:141], v[18:33]
	global_load_dwordx4 v[110:113], v77, s[2:3] offset:640
	global_load_dwordx4 v[114:117], v77, s[4:5] offset:640
	s_waitcnt lgkmcnt(3)
	v_mfma_f32_32x32x16_bf16 v[34:49], v[118:121], v[130:133], v[34:49]
	s_waitcnt vmcnt(9)
	ds_write_b128 v75, v[82:85] offset:13824
	s_waitcnt vmcnt(8)
	ds_write_b128 v75, v[98:101] offset:32256
	v_mfma_f32_32x32x16_bf16 v[2:17], v[126:129], v[130:133], v[2:17]
	s_waitcnt lgkmcnt(4)
	v_mfma_f32_32x32x16_bf16 v[50:65], v[118:121], v[134:137], v[50:65]
	v_mfma_f32_32x32x16_bf16 v[18:33], v[126:129], v[134:137], v[18:33]
	s_waitcnt lgkmcnt(0)
	s_barrier
	ds_read_b128 v[82:85], v73
	ds_read_b128 v[98:101], v74 offset:18432
	ds_read_b128 v[118:121], v73 offset:32
	ds_read_b128 v[122:125], v74 offset:18464
	ds_read_b128 v[126:129], v73 offset:4608
	ds_read_b128 v[130:133], v73 offset:4640
	s_waitcnt lgkmcnt(4)
	v_mfma_f32_32x32x16_bf16 v[34:49], v[82:85], v[98:101], v[34:49]
	s_waitcnt lgkmcnt(1)
	v_mfma_f32_32x32x16_bf16 v[2:17], v[126:129], v[98:101], v[2:17]
	ds_read_b128 v[98:101], v74 offset:23040
	ds_read_b128 v[134:137], v74 offset:23072
	s_waitcnt lgkmcnt(1)
	v_mfma_f32_32x32x16_bf16 v[50:65], v[82:85], v[98:101], v[50:65]
	global_load_dwordx4 v[82:85], v80, s[2:3] offset:768
	global_load_dwordx4 v[138:141], v80, s[4:5] offset:768
	s_waitcnt vmcnt(9)
	ds_write_b128 v75, v[86:89] offset:36864
	s_waitcnt vmcnt(8)
	ds_write_b128 v75, v[142:145] offset:55296
	v_mfma_f32_32x32x16_bf16 v[18:33], v[126:129], v[98:101], v[18:33]
	global_load_dwordx4 v[86:89], v79, s[2:3] offset:768
	global_load_dwordx4 v[98:101], v79, s[4:5] offset:768
	v_mfma_f32_32x32x16_bf16 v[34:49], v[118:121], v[122:125], v[34:49]
	v_mfma_f32_32x32x16_bf16 v[2:17], v[130:133], v[122:125], v[2:17]
	s_waitcnt lgkmcnt(2)
	v_mfma_f32_32x32x16_bf16 v[50:65], v[118:121], v[134:137], v[50:65]
	ds_read_b128 v[118:121], v73 offset:64
	ds_read_b128 v[122:125], v73 offset:4672
	ds_read_b128 v[126:129], v74 offset:18496
	ds_read_b128 v[142:145], v74 offset:23104
	s_waitcnt vmcnt(9)
	ds_write_b128 v75, v[90:93] offset:41472
	s_waitcnt vmcnt(8)
	ds_write_b128 v75, v[102:105] offset:59904
	v_mfma_f32_32x32x16_bf16 v[18:33], v[130:133], v[134:137], v[18:33]
	global_load_dwordx4 v[90:93], v78, s[2:3] offset:768
	global_load_dwordx4 v[102:105], v78, s[4:5] offset:768
	s_waitcnt lgkmcnt(3)
	v_mfma_f32_32x32x16_bf16 v[34:49], v[118:121], v[126:129], v[34:49]
	v_mfma_f32_32x32x16_bf16 v[2:17], v[122:125], v[126:129], v[2:17]
	s_waitcnt lgkmcnt(2)
	v_mfma_f32_32x32x16_bf16 v[50:65], v[118:121], v[142:145], v[50:65]
	ds_read_b128 v[118:121], v73 offset:96
	ds_read_b128 v[126:129], v73 offset:4704
	ds_read_b128 v[130:133], v74 offset:18528
	ds_read_b128 v[134:137], v74 offset:23136
	s_waitcnt vmcnt(9)
	ds_write_b128 v75, v[94:97] offset:46080
	s_waitcnt vmcnt(8)
	ds_write_b128 v75, v[106:109] offset:64512
	v_mfma_f32_32x32x16_bf16 v[18:33], v[122:125], v[142:145], v[18:33]
	global_load_dwordx4 v[94:97], v77, s[2:3] offset:768
	global_load_dwordx4 v[106:109], v77, s[4:5] offset:768
	s_waitcnt lgkmcnt(3)
	v_mfma_f32_32x32x16_bf16 v[34:49], v[118:121], v[130:133], v[34:49]
	s_waitcnt vmcnt(9)
	ds_write_b128 v75, v[110:113] offset:50688
	s_waitcnt vmcnt(8)
	ds_write_b128 v76, v[114:117] offset:13824
	v_mfma_f32_32x32x16_bf16 v[2:17], v[126:129], v[130:133], v[2:17]
	s_waitcnt lgkmcnt(4)
	v_mfma_f32_32x32x16_bf16 v[50:65], v[118:121], v[134:137], v[50:65]
	v_mfma_f32_32x32x16_bf16 v[18:33], v[126:129], v[134:137], v[18:33]
	s_waitcnt lgkmcnt(0)
	s_barrier
; #define GL1_(RA, RB, i) { RA[i] = *(const u32x4*)(ap + (aoff + (i) * astep)); if ((i) < NB) RB[(i) < NB ? (i) : 0] = *(const u32x4*)(bp + (boff + (i) * bstep)); }
; #define LS1_(RA, RB, ST, i) { char* sn_ = lds + (ST) * STAGE; *(u32x4*)(sn_ + wofs + (i) * 32 * LROW) = RA[i]; \
;                               if ((i) < NB) *(u32x4*)(sn_ + STAGE_OP + wofs + (i) * 32 * LROW) = RB[(i) < NB ? (i) : 0]; }
; template <int NJ> DI void gemm_mainloop_reg(const bf16_t* __restrict__ A, int lda, const bf16_t* __restrict__ Bt, int ldb, int K, f32x16 (&acc)[2][NJ], char* lds) {
;     ...
; #pragma unroll
;   for (int i = 0; i < 4; ++i) GL1_(ra0, rb0, i);
;   ap += 128; bp += 128;
; #pragma unroll
;   for (int i = 0; i < 4; ++i) GL1_(ra1, rb1, i);
;   ap += 128; bp += 128;
; #pragma unroll
;   for (int i = 0; i < 4; ++i) LS1_(ra0, rb0, 0, i);
;   __syncthreads();
;   const int nk = K >> 6;
;   for (int kt = 0; kt < nk; kt += 2) {
;     const bool l0 = (kt + 2 < nk), l1 = (kt + 3 < nk);
;     STEP_(0, l0, ra0, rb0, true, ra1, rb1);
;     __syncthreads();
;     STEP_(1, l1, ra1, rb1, l0, ra0, rb0);
;     __syncthreads();
;   }
	ds_read_b128 v[110:113], v73 offset:36864
	ds_read_b128 v[114:117], v74 offset:55296
	ds_read_b128 v[118:121], v73 offset:36896
	ds_read_b128 v[122:125], v74 offset:55328
	ds_read_b128 v[126:129], v73 offset:41472
	ds_read_b128 v[130:133], v73 offset:41504
	s_waitcnt lgkmcnt(4)
	v_mfma_f32_32x32x16_bf16 v[34:49], v[110:113], v[114:117], v[34:49]
	s_waitcnt lgkmcnt(1)
	v_mfma_f32_32x32x16_bf16 v[2:17], v[126:129], v[114:117], v[2:17]
	ds_read_b128 v[114:117], v74 offset:59904
	ds_read_b128 v[134:137], v74 offset:59936
	s_waitcnt lgkmcnt(1)
	v_mfma_f32_32x32x16_bf16 v[50:65], v[110:113], v[114:117], v[50:65]
	global_load_dwordx4 v[110:113], v80, s[2:3] offset:896
	global_load_dwordx4 v[142:145], v80, s[4:5] offset:896
	s_waitcnt vmcnt(9)
	ds_write_b128 v75, v[82:85]
	s_waitcnt vmcnt(8)
	ds_write_b128 v75, v[138:141] offset:18432
	v_mfma_f32_32x32x16_bf16 v[18:33], v[126:129], v[114:117], v[18:33]
	global_load_dwordx4 v[82:85], v79, s[2:3] offset:896
	global_load_dwordx4 v[114:117], v79, s[4:5] offset:896
	v_mfma_f32_32x32x16_bf16 v[34:49], v[118:121], v[122:125], v[34:49]
	v_mfma_f32_32x32x16_bf16 v[2:17], v[130:133], v[122:125], v[2:17]
	s_waitcnt lgkmcnt(2)
	v_mfma_f32_32x32x16_bf16 v[50:65], v[118:121], v[134:137], v[50:65]
	ds_read_b128 v[118:121], v73 offset:36928
	ds_read_b128 v[122:125], v73 offset:41536
	ds_read_b128 v[126:129], v74 offset:55360
	ds_read_b128 v[138:141], v74 offset:59968
	s_waitcnt vmcnt(9)
	ds_write_b128 v75, v[86:89] offset:4608
	s_waitcnt vmcnt(8)
	ds_write_b128 v75, v[98:101] offset:23040
	v_mfma_f32_32x32x16_bf16 v[18:33], v[130:133], v[134:137], v[18:33]
	global_load_dwordx4 v[86:89], v78, s[2:3] offset:896
	global_load_dwordx4 v[98:101], v78, s[4:5] offset:896
	s_waitcnt lgkmcnt(3)
	v_mfma_f32_32x32x16_bf16 v[34:49], v[118:121], v[126:129], v[34:49]
	v_mfma_f32_32x32x16_bf16 v[2:17], v[122:125], v[126:129], v[2:17]
	s_waitcnt lgkmcnt(2)
	v_mfma_f32_32x32x16_bf16 v[50:65], v[118:121], v[138:141], v[50:65]
	ds_read_b128 v[118:121], v73 offset:36960
	ds_read_b128 v[126:129], v73 offset:41568
	ds_read_b128 v[130:133], v74 offset:55392
	ds_read_b128 v[134:137], v74 offset:60000
	s_waitcnt vmcnt(9)
	ds_write_b128 v75, v[90:93] offset:9216
	s_waitcnt vmcnt(8)
	ds_write_b128 v75, v[102:105] offset:27648
	v_mfma_f32_32x32x16_bf16 v[18:33], v[122:125], v[138:141], v[18:33]
	global_load_dwordx4 v[90:93], v77, s[2:3] offset:896
	global_load_dwordx4 v[102:105], v77, s[4:5] offset:896
	s_waitcnt lgkmcnt(3)
	v_mfma_f32_32x32x16_bf16 v[34:49], v[118:121], v[130:133], v[34:49]
	s_waitcnt vmcnt(9)
	ds_write_b128 v75, v[94:97] offset:13824
	s_waitcnt vmcnt(8)
	ds_write_b128 v75, v[106:109] offset:32256
	v_mfma_f32_32x32x16_bf16 v[2:17], v[126:129], v[130:133], v[2:17]
	s_waitcnt lgkmcnt(4)
	v_mfma_f32_32x32x16_bf16 v[50:65], v[118:121], v[134:137], v[50:65]
	v_mfma_f32_32x32x16_bf16 v[18:33], v[126:129], v[134:137], v[18:33]
	s_waitcnt lgkmcnt(0)
	s_barrier
	ds_read_b128 v[94:97], v73
	ds_read_b128 v[106:109], v74 offset:18432
	ds_read_b128 v[118:121], v73 offset:32
	ds_read_b128 v[122:125], v74 offset:18464
	ds_read_b128 v[126:129], v73 offset:4608
	ds_read_b128 v[130:133], v73 offset:4640
	s_waitcnt lgkmcnt(4)
	v_mfma_f32_32x32x16_bf16 v[34:49], v[94:97], v[106:109], v[34:49]
	s_waitcnt lgkmcnt(1)
	v_mfma_f32_32x32x16_bf16 v[2:17], v[126:129], v[106:109], v[2:17]
	ds_read_b128 v[106:109], v74 offset:23040
	ds_read_b128 v[134:137], v74 offset:23072
	s_waitcnt lgkmcnt(1)
	v_mfma_f32_32x32x16_bf16 v[50:65], v[94:97], v[106:109], v[50:65]
	global_load_dwordx4 v[94:97], v80, s[2:3] offset:1024
	global_load_dwordx4 v[138:141], v80, s[4:5] offset:1024
	s_waitcnt vmcnt(9)
	ds_write_b128 v75, v[110:113] offset:36864
	s_waitcnt vmcnt(8)
	ds_write_b128 v75, v[142:145] offset:55296
	v_mfma_f32_32x32x16_bf16 v[18:33], v[126:129], v[106:109], v[18:33]
	global_load_dwordx4 v[106:109], v79, s[2:3] offset:1024
	global_load_dwordx4 v[110:113], v79, s[4:5] offset:1024
	v_mfma_f32_32x32x16_bf16 v[34:49], v[118:121], v[122:125], v[34:49]
	v_mfma_f32_32x32x16_bf16 v[2:17], v[130:133], v[122:125], v[2:17]
	s_waitcnt lgkmcnt(2)
	v_mfma_f32_32x32x16_bf16 v[50:65], v[118:121], v[134:137], v[50:65]
	ds_read_b128 v[118:121], v73 offset:64
	ds_read_b128 v[122:125], v73 offset:4672
	ds_read_b128 v[126:129], v74 offset:18496
	ds_read_b128 v[142:145], v74 offset:23104
	s_waitcnt vmcnt(9)
	ds_write_b128 v75, v[82:85] offset:41472
	s_waitcnt vmcnt(8)
	ds_write_b128 v75, v[114:117] offset:59904
	v_mfma_f32_32x32x16_bf16 v[18:33], v[130:133], v[134:137], v[18:33]
	global_load_dwordx4 v[82:85], v78, s[2:3] offset:1024
	global_load_dwordx4 v[114:117], v78, s[4:5] offset:1024
	s_waitcnt lgkmcnt(3)
	v_mfma_f32_32x32x16_bf16 v[34:49], v[118:121], v[126:129], v[34:49]
	v_mfma_f32_32x32x16_bf16 v[2:17], v[122:125], v[126:129], v[2:17]
	s_waitcnt lgkmcnt(2)
	v_mfma_f32_32x32x16_bf16 v[50:65], v[118:121], v[142:145], v[50:65]
	ds_read_b128 v[118:121], v73 offset:96
	ds_read_b128 v[126:129], v73 offset:4704
	ds_read_b128 v[130:133], v74 offset:18528
	ds_read_b128 v[134:137], v74 offset:23136
	s_waitcnt vmcnt(9)
	ds_write_b128 v75, v[86:89] offset:46080
	s_waitcnt vmcnt(8)
	ds_write_b128 v75, v[98:101] offset:64512
	v_mfma_f32_32x32x16_bf16 v[18:33], v[122:125], v[142:145], v[18:33]
	global_load_dwordx4 v[86:89], v77, s[2:3] offset:1024
	global_load_dwordx4 v[98:101], v77, s[4:5] offset:1024
	s_waitcnt lgkmcnt(3)
	v_mfma_f32_32x32x16_bf16 v[34:49], v[118:121], v[130:133], v[34:49]
	s_waitcnt vmcnt(9)
	ds_write_b128 v75, v[90:93] offset:50688
	s_waitcnt vmcnt(8)
	ds_write_b128 v76, v[102:105] offset:13824
	v_mfma_f32_32x32x16_bf16 v[2:17], v[126:129], v[130:133], v[2:17]
	s_waitcnt lgkmcnt(4)
	v_mfma_f32_32x32x16_bf16 v[50:65], v[118:121], v[134:137], v[50:65]
	v_mfma_f32_32x32x16_bf16 v[18:33], v[126:129], v[134:137], v[18:33]
	s_waitcnt lgkmcnt(0)
	s_barrier
; #define GL1_(RA, RB, i) { RA[i] = *(const u32x4*)(ap + (aoff + (i) * astep)); if ((i) < NB) RB[(i) < NB ? (i) : 0] = *(const u32x4*)(bp + (boff + (i) * bstep)); }
; #define LS1_(RA, RB, ST, i) { char* sn_ = lds + (ST) * STAGE; *(u32x4*)(sn_ + wofs + (i) * 32 * LROW) = RA[i]; \
;                               if ((i) < NB) *(u32x4*)(sn_ + STAGE_OP + wofs + (i) * 32 * LROW) = RB[(i) < NB ? (i) : 0]; }
; template <int NJ> DI void gemm_mainloop_reg(const bf16_t* __restrict__ A, int lda, const bf16_t* __restrict__ Bt, int ldb, int K, f32x16 (&acc)[2][NJ], char* lds) {
;     ...
; #pragma unroll
;   for (int i = 0; i < 4; ++i) GL1_(ra0, rb0, i);
;   ap += 128; bp += 128;
; #pragma unroll
;   for (int i = 0; i < 4; ++i) GL1_(ra1, rb1, i);
;   ap += 128; bp += 128;
; #pragma unroll
;   for (int i = 0; i < 4; ++i) LS1_(ra0, rb0, 0, i);
;   __syncthreads();
;   const int nk = K >> 6;
;   for (int kt = 0; kt < nk; kt += 2) {
;     const bool l0 = (kt + 2 < nk), l1 = (kt + 3 < nk);
;     STEP_(0, l0, ra0, rb0, true, ra1, rb1);
;     __syncthreads();
;     STEP_(1, l1, ra1, rb1, l0, ra0, rb0);
;     __syncthreads();
;   }
	ds_read_b128 v[90:93], v73 offset:36864
	ds_read_b128 v[102:105], v74 offset:55296
	ds_read_b128 v[118:121], v73 offset:36896
	ds_read_b128 v[122:125], v74 offset:55328
	ds_read_b128 v[126:129], v73 offset:41472
	ds_read_b128 v[130:133], v73 offset:41504
	s_waitcnt lgkmcnt(4)
	v_mfma_f32_32x32x16_bf16 v[34:49], v[90:93], v[102:105], v[34:49]
	s_waitcnt lgkmcnt(1)
	v_mfma_f32_32x32x16_bf16 v[2:17], v[126:129], v[102:105], v[2:17]
	ds_read_b128 v[102:105], v74 offset:59904
	ds_read_b128 v[134:137], v74 offset:59936
	s_waitcnt lgkmcnt(1)
	v_mfma_f32_32x32x16_bf16 v[50:65], v[90:93], v[102:105], v[50:65]
	global_load_dwordx4 v[90:93], v80, s[2:3] offset:1152
	global_load_dwordx4 v[142:145], v80, s[4:5] offset:1152
	s_waitcnt vmcnt(9)
	ds_write_b128 v75, v[94:97]
	s_waitcnt vmcnt(8)
	ds_write_b128 v75, v[138:141] offset:18432
	v_mfma_f32_32x32x16_bf16 v[18:33], v[126:129], v[102:105], v[18:33]
	global_load_dwordx4 v[94:97], v79, s[2:3] offset:1152
	global_load_dwordx4 v[102:105], v79, s[4:5] offset:1152
	v_mfma_f32_32x32x16_bf16 v[34:49], v[118:121], v[122:125], v[34:49]
	v_mfma_f32_32x32x16_bf16 v[2:17], v[130:133], v[122:125], v[2:17]
	s_waitcnt lgkmcnt(2)
	v_mfma_f32_32x32x16_bf16 v[50:65], v[118:121], v[134:137], v[50:65]
	ds_read_b128 v[118:121], v73 offset:36928
	ds_read_b128 v[122:125], v73 offset:41536
	ds_read_b128 v[126:129], v74 offset:55360
	ds_read_b128 v[138:141], v74 offset:59968
	s_waitcnt vmcnt(9)
	ds_write_b128 v75, v[106:109] offset:4608
	s_waitcnt vmcnt(8)
	ds_write_b128 v75, v[110:113] offset:23040
	v_mfma_f32_32x32x16_bf16 v[18:33], v[130:133], v[134:137], v[18:33]
	global_load_dwordx4 v[106:109], v78, s[2:3] offset:1152
	global_load_dwordx4 v[110:113], v78, s[4:5] offset:1152
	s_waitcnt lgkmcnt(3)
	v_mfma_f32_32x32x16_bf16 v[34:49], v[118:121], v[126:129], v[34:49]
	v_mfma_f32_32x32x16_bf16 v[2:17], v[122:125], v[126:129], v[2:17]
	s_waitcnt lgkmcnt(2)
	v_mfma_f32_32x32x16_bf16 v[50:65], v[118:121], v[138:141], v[50:65]
	ds_read_b128 v[118:121], v73 offset:36960
	ds_read_b128 v[126:129], v73 offset:41568
	ds_read_b128 v[130:133], v74 offset:55392
	ds_read_b128 v[134:137], v74 offset:60000
	s_waitcnt vmcnt(9)
	ds_write_b128 v75, v[82:85] offset:9216
	s_waitcnt vmcnt(8)
	ds_write_b128 v75, v[114:117] offset:27648
	v_mfma_f32_32x32x16_bf16 v[18:33], v[122:125], v[138:141], v[18:33]
	global_load_dwordx4 v[82:85], v77, s[2:3] offset:1152
	global_load_dwordx4 v[114:117], v77, s[4:5] offset:1152
	s_waitcnt lgkmcnt(3)
	v_mfma_f32_32x32x16_bf16 v[34:49], v[118:121], v[130:133], v[34:49]
	s_waitcnt vmcnt(9)
	ds_write_b128 v75, v[86:89] offset:13824
	s_waitcnt vmcnt(8)
	ds_write_b128 v75, v[98:101] offset:32256
	v_mfma_f32_32x32x16_bf16 v[2:17], v[126:129], v[130:133], v[2:17]
	s_waitcnt lgkmcnt(4)
	v_mfma_f32_32x32x16_bf16 v[50:65], v[118:121], v[134:137], v[50:65]
	v_mfma_f32_32x32x16_bf16 v[18:33], v[126:129], v[134:137], v[18:33]
	s_waitcnt lgkmcnt(0)
	s_barrier
	ds_read_b128 v[86:89], v73
	ds_read_b128 v[98:101], v74 offset:18432
	ds_read_b128 v[118:121], v73 offset:32
	ds_read_b128 v[122:125], v74 offset:18464
	ds_read_b128 v[126:129], v73 offset:4608
	ds_read_b128 v[130:133], v73 offset:4640
	s_waitcnt lgkmcnt(4)
	v_mfma_f32_32x32x16_bf16 v[34:49], v[86:89], v[98:101], v[34:49]
	s_waitcnt lgkmcnt(1)
	v_mfma_f32_32x32x16_bf16 v[2:17], v[126:129], v[98:101], v[2:17]
	ds_read_b128 v[98:101], v74 offset:23040
	ds_read_b128 v[134:137], v74 offset:23072
	s_waitcnt lgkmcnt(1)
	v_mfma_f32_32x32x16_bf16 v[50:65], v[86:89], v[98:101], v[50:65]
	global_load_dwordx4 v[86:89], v80, s[2:3] offset:1280
	global_load_dwordx4 v[138:141], v80, s[4:5] offset:1280
	s_waitcnt vmcnt(9)
	ds_write_b128 v75, v[90:93] offset:36864
	s_waitcnt vmcnt(8)
	ds_write_b128 v75, v[142:145] offset:55296
	v_mfma_f32_32x32x16_bf16 v[18:33], v[126:129], v[98:101], v[18:33]
	global_load_dwordx4 v[90:93], v79, s[2:3] offset:1280
	global_load_dwordx4 v[98:101], v79, s[4:5] offset:1280
	v_mfma_f32_32x32x16_bf16 v[34:49], v[118:121], v[122:125], v[34:49]
	v_mfma_f32_32x32x16_bf16 v[2:17], v[130:133], v[122:125], v[2:17]
	s_waitcnt lgkmcnt(2)
	v_mfma_f32_32x32x16_bf16 v[50:65], v[118:121], v[134:137], v[50:65]
	ds_read_b128 v[118:121], v73 offset:64
	ds_read_b128 v[122:125], v73 offset:4672
	ds_read_b128 v[126:129], v74 offset:18496
	ds_read_b128 v[142:145], v74 offset:23104
	s_waitcnt vmcnt(9)
	ds_write_b128 v75, v[94:97] offset:41472
	s_waitcnt vmcnt(8)
	ds_write_b128 v75, v[102:105] offset:59904
	v_mfma_f32_32x32x16_bf16 v[18:33], v[130:133], v[134:137], v[18:33]
	global_load_dwordx4 v[94:97], v78, s[2:3] offset:1280
	global_load_dwordx4 v[102:105], v78, s[4:5] offset:1280
	s_waitcnt lgkmcnt(3)
	v_mfma_f32_32x32x16_bf16 v[34:49], v[118:121], v[126:129], v[34:49]
	v_mfma_f32_32x32x16_bf16 v[2:17], v[122:125], v[126:129], v[2:17]
	s_waitcnt lgkmcnt(2)
	v_mfma_f32_32x32x16_bf16 v[50:65], v[118:121], v[142:145], v[50:65]
	ds_read_b128 v[118:121], v73 offset:96
	ds_read_b128 v[126:129], v73 offset:4704
	ds_read_b128 v[130:133], v74 offset:18528
	ds_read_b128 v[134:137], v74 offset:23136
	s_waitcnt vmcnt(9)
	ds_write_b128 v75, v[106:109] offset:46080
	s_waitcnt vmcnt(8)
	ds_write_b128 v75, v[110:113] offset:64512
	v_mfma_f32_32x32x16_bf16 v[18:33], v[122:125], v[142:145], v[18:33]
	global_load_dwordx4 v[106:109], v77, s[2:3] offset:1280
	global_load_dwordx4 v[110:113], v77, s[4:5] offset:1280
	s_waitcnt lgkmcnt(3)
	v_mfma_f32_32x32x16_bf16 v[34:49], v[118:121], v[130:133], v[34:49]
	s_waitcnt vmcnt(9)
	ds_write_b128 v75, v[82:85] offset:50688
	s_waitcnt vmcnt(8)
	ds_write_b128 v76, v[114:117] offset:13824
	v_mfma_f32_32x32x16_bf16 v[2:17], v[126:129], v[130:133], v[2:17]
	s_waitcnt lgkmcnt(4)
	v_mfma_f32_32x32x16_bf16 v[50:65], v[118:121], v[134:137], v[50:65]
	v_mfma_f32_32x32x16_bf16 v[18:33], v[126:129], v[134:137], v[18:33]
	s_waitcnt lgkmcnt(0)
	s_barrier
; #define GL1_(RA, RB, i) { RA[i] = *(const u32x4*)(ap + (aoff + (i) * astep)); if ((i) < NB) RB[(i) < NB ? (i) : 0] = *(const u32x4*)(bp + (boff + (i) * bstep)); }
; #define LS1_(RA, RB, ST, i) { char* sn_ = lds + (ST) * STAGE; *(u32x4*)(sn_ + wofs + (i) * 32 * LROW) = RA[i]; \
;                               if ((i) < NB) *(u32x4*)(sn_ + STAGE_OP + wofs + (i) * 32 * LROW) = RB[(i) < NB ? (i) : 0]; }
; template <int NJ> DI void gemm_mainloop_reg(const bf16_t* __restrict__ A, int lda, const bf16_t* __restrict__ Bt, int ldb, int K, f32x16 (&acc)[2][NJ], char* lds) {
;     ...
; #pragma unroll
;   for (int i = 0; i < 4; ++i) GL1_(ra0, rb0, i);
;   ap += 128; bp += 128;
; #pragma unroll
;   for (int i = 0; i < 4; ++i) GL1_(ra1, rb1, i);
;   ap += 128; bp += 128;
; #pragma unroll
;   for (int i = 0; i < 4; ++i) LS1_(ra0, rb0, 0, i);
;   __syncthreads();
;   const int nk = K >> 6;
;   for (int kt = 0; kt < nk; kt += 2) {
;     const bool l0 = (kt + 2 < nk), l1 = (kt + 3 < nk);
;     STEP_(0, l0, ra0, rb0, true, ra1, rb1);
;     __syncthreads();
;     STEP_(1, l1, ra1, rb1, l0, ra0, rb0);
;     __syncthreads();
;   }
	ds_read_b128 v[82:85], v73 offset:36864
	ds_read_b128 v[114:117], v74 offset:55296
	ds_read_b128 v[118:121], v73 offset:36896
	ds_read_b128 v[122:125], v74 offset:55328
	ds_read_b128 v[126:129], v73 offset:41472
	ds_read_b128 v[130:133], v73 offset:41504
	s_waitcnt lgkmcnt(4)
	v_mfma_f32_32x32x16_bf16 v[34:49], v[82:85], v[114:117], v[34:49]
	s_waitcnt lgkmcnt(1)
	v_mfma_f32_32x32x16_bf16 v[2:17], v[126:129], v[114:117], v[2:17]
	ds_read_b128 v[114:117], v74 offset:59904
	ds_read_b128 v[134:137], v74 offset:59936
	s_waitcnt lgkmcnt(1)
	v_mfma_f32_32x32x16_bf16 v[50:65], v[82:85], v[114:117], v[50:65]
	global_load_dwordx4 v[82:85], v80, s[2:3] offset:1408
	global_load_dwordx4 v[142:145], v80, s[4:5] offset:1408
	s_waitcnt vmcnt(9)
	ds_write_b128 v75, v[86:89]
	s_waitcnt vmcnt(8)
	ds_write_b128 v75, v[138:141] offset:18432
	v_mfma_f32_32x32x16_bf16 v[18:33], v[126:129], v[114:117], v[18:33]
	global_load_dwordx4 v[86:89], v79, s[2:3] offset:1408
	global_load_dwordx4 v[114:117], v79, s[4:5] offset:1408
	v_mfma_f32_32x32x16_bf16 v[34:49], v[118:121], v[122:125], v[34:49]
	v_mfma_f32_32x32x16_bf16 v[2:17], v[130:133], v[122:125], v[2:17]
	s_waitcnt lgkmcnt(2)
	v_mfma_f32_32x32x16_bf16 v[50:65], v[118:121], v[134:137], v[50:65]
	ds_read_b128 v[118:121], v73 offset:36928
	ds_read_b128 v[122:125], v73 offset:41536
	ds_read_b128 v[126:129], v74 offset:55360
	ds_read_b128 v[138:141], v74 offset:59968
	s_waitcnt vmcnt(9)
	ds_write_b128 v75, v[90:93] offset:4608
	s_waitcnt vmcnt(8)
	ds_write_b128 v75, v[98:101] offset:23040
	v_mfma_f32_32x32x16_bf16 v[18:33], v[130:133], v[134:137], v[18:33]
	global_load_dwordx4 v[90:93], v78, s[2:3] offset:1408
	global_load_dwordx4 v[98:101], v78, s[4:5] offset:1408
	s_waitcnt lgkmcnt(3)
	v_mfma_f32_32x32x16_bf16 v[34:49], v[118:121], v[126:129], v[34:49]
	v_mfma_f32_32x32x16_bf16 v[2:17], v[122:125], v[126:129], v[2:17]
	s_waitcnt lgkmcnt(2)
	v_mfma_f32_32x32x16_bf16 v[50:65], v[118:121], v[138:141], v[50:65]
	ds_read_b128 v[118:121], v73 offset:36960
	ds_read_b128 v[126:129], v73 offset:41568
	ds_read_b128 v[130:133], v74 offset:55392
	ds_read_b128 v[134:137], v74 offset:60000
	s_waitcnt vmcnt(9)
	ds_write_b128 v75, v[94:97] offset:9216
	s_waitcnt vmcnt(8)
	ds_write_b128 v75, v[102:105] offset:27648
	v_mfma_f32_32x32x16_bf16 v[18:33], v[122:125], v[138:141], v[18:33]
	global_load_dwordx4 v[94:97], v77, s[2:3] offset:1408
	global_load_dwordx4 v[102:105], v77, s[4:5] offset:1408
	s_waitcnt lgkmcnt(3)
	v_mfma_f32_32x32x16_bf16 v[34:49], v[118:121], v[130:133], v[34:49]
	s_waitcnt vmcnt(9)
	ds_write_b128 v75, v[106:109] offset:13824
	s_waitcnt vmcnt(8)
	ds_write_b128 v75, v[110:113] offset:32256
	v_mfma_f32_32x32x16_bf16 v[2:17], v[126:129], v[130:133], v[2:17]
	s_waitcnt lgkmcnt(4)
	v_mfma_f32_32x32x16_bf16 v[50:65], v[118:121], v[134:137], v[50:65]
	v_mfma_f32_32x32x16_bf16 v[18:33], v[126:129], v[134:137], v[18:33]
	s_waitcnt lgkmcnt(0)
	s_barrier
	ds_read_b128 v[106:109], v73
	ds_read_b128 v[110:113], v74 offset:18432
	ds_read_b128 v[118:121], v73 offset:32
	ds_read_b128 v[122:125], v74 offset:18464
	ds_read_b128 v[126:129], v73 offset:4608
	ds_read_b128 v[130:133], v73 offset:4640
	s_waitcnt lgkmcnt(4)
	v_mfma_f32_32x32x16_bf16 v[34:49], v[106:109], v[110:113], v[34:49]
	s_waitcnt lgkmcnt(1)
	v_mfma_f32_32x32x16_bf16 v[2:17], v[126:129], v[110:113], v[2:17]
	ds_read_b128 v[110:113], v74 offset:23040
	ds_read_b128 v[134:137], v74 offset:23072
	s_waitcnt lgkmcnt(1)
	v_mfma_f32_32x32x16_bf16 v[50:65], v[106:109], v[110:113], v[50:65]
	global_load_dwordx4 v[106:109], v80, s[2:3] offset:1536
	global_load_dwordx4 v[138:141], v80, s[4:5] offset:1536
	s_waitcnt vmcnt(9)
	ds_write_b128 v75, v[82:85] offset:36864
	s_waitcnt vmcnt(8)
	ds_write_b128 v75, v[142:145] offset:55296
	v_mfma_f32_32x32x16_bf16 v[18:33], v[126:129], v[110:113], v[18:33]
	global_load_dwordx4 v[82:85], v79, s[2:3] offset:1536
	global_load_dwordx4 v[110:113], v79, s[4:5] offset:1536
	v_mfma_f32_32x32x16_bf16 v[34:49], v[118:121], v[122:125], v[34:49]
	v_mfma_f32_32x32x16_bf16 v[2:17], v[130:133], v[122:125], v[2:17]
	s_waitcnt lgkmcnt(2)
	v_mfma_f32_32x32x16_bf16 v[50:65], v[118:121], v[134:137], v[50:65]
	ds_read_b128 v[118:121], v73 offset:64
	ds_read_b128 v[122:125], v73 offset:4672
	ds_read_b128 v[126:129], v74 offset:18496
	ds_read_b128 v[142:145], v74 offset:23104
	s_waitcnt vmcnt(9)
	ds_write_b128 v75, v[86:89] offset:41472
	s_waitcnt vmcnt(8)
	ds_write_b128 v75, v[114:117] offset:59904
	v_mfma_f32_32x32x16_bf16 v[18:33], v[130:133], v[134:137], v[18:33]
	global_load_dwordx4 v[86:89], v78, s[2:3] offset:1536
	global_load_dwordx4 v[114:117], v78, s[4:5] offset:1536
	s_waitcnt lgkmcnt(3)
	v_mfma_f32_32x32x16_bf16 v[34:49], v[118:121], v[126:129], v[34:49]
	v_mfma_f32_32x32x16_bf16 v[2:17], v[122:125], v[126:129], v[2:17]
	s_waitcnt lgkmcnt(2)
	v_mfma_f32_32x32x16_bf16 v[50:65], v[118:121], v[142:145], v[50:65]
	ds_read_b128 v[118:121], v73 offset:96
	ds_read_b128 v[126:129], v73 offset:4704
	ds_read_b128 v[130:133], v74 offset:18528
	ds_read_b128 v[134:137], v74 offset:23136
	s_waitcnt vmcnt(9)
	ds_write_b128 v75, v[90:93] offset:46080
	s_waitcnt vmcnt(8)
	ds_write_b128 v75, v[98:101] offset:64512
	v_mfma_f32_32x32x16_bf16 v[18:33], v[122:125], v[142:145], v[18:33]
	global_load_dwordx4 v[90:93], v77, s[2:3] offset:1536
	global_load_dwordx4 v[98:101], v77, s[4:5] offset:1536
	s_waitcnt lgkmcnt(3)
	v_mfma_f32_32x32x16_bf16 v[34:49], v[118:121], v[130:133], v[34:49]
	s_waitcnt vmcnt(9)
	ds_write_b128 v75, v[94:97] offset:50688
	s_waitcnt vmcnt(8)
	ds_write_b128 v76, v[102:105] offset:13824
	v_mfma_f32_32x32x16_bf16 v[2:17], v[126:129], v[130:133], v[2:17]
	s_waitcnt lgkmcnt(4)
	v_mfma_f32_32x32x16_bf16 v[50:65], v[118:121], v[134:137], v[50:65]
	v_mfma_f32_32x32x16_bf16 v[18:33], v[126:129], v[134:137], v[18:33]
	s_waitcnt lgkmcnt(0)
	s_barrier
; #define GL1_(RA, RB, i) { RA[i] = *(const u32x4*)(ap + (aoff + (i) * astep)); if ((i) < NB) RB[(i) < NB ? (i) : 0] = *(const u32x4*)(bp + (boff + (i) * bstep)); }
; #define LS1_(RA, RB, ST, i) { char* sn_ = lds + (ST) * STAGE; *(u32x4*)(sn_ + wofs + (i) * 32 * LROW) = RA[i]; \
;                               if ((i) < NB) *(u32x4*)(sn_ + STAGE_OP + wofs + (i) * 32 * LROW) = RB[(i) < NB ? (i) : 0]; }
; template <int NJ> DI void gemm_mainloop_reg(const bf16_t* __restrict__ A, int lda, const bf16_t* __restrict__ Bt, int ldb, int K, f32x16 (&acc)[2][NJ], char* lds) {
;     ...
; #pragma unroll
;   for (int i = 0; i < 4; ++i) GL1_(ra0, rb0, i);
;   ap += 128; bp += 128;
; #pragma unroll
;   for (int i = 0; i < 4; ++i) GL1_(ra1, rb1, i);
;   ap += 128; bp += 128;
; #pragma unroll
;   for (int i = 0; i < 4; ++i) LS1_(ra0, rb0, 0, i);
;   __syncthreads();
;   const int nk = K >> 6;
;   for (int kt = 0; kt < nk; kt += 2) {
;     const bool l0 = (kt + 2 < nk), l1 = (kt + 3 < nk);
;     STEP_(0, l0, ra0, rb0, true, ra1, rb1);
;     __syncthreads();
;     STEP_(1, l1, ra1, rb1, l0, ra0, rb0);
;     __syncthreads();
;   }
	ds_read_b128 v[94:97], v73 offset:36864
	ds_read_b128 v[102:105], v74 offset:55296
	ds_read_b128 v[118:121], v73 offset:36896
	ds_read_b128 v[122:125], v74 offset:55328
	ds_read_b128 v[126:129], v73 offset:41472
	ds_read_b128 v[130:133], v73 offset:41504
	s_waitcnt lgkmcnt(4)
	v_mfma_f32_32x32x16_bf16 v[34:49], v[94:97], v[102:105], v[34:49]
	s_waitcnt lgkmcnt(1)
	v_mfma_f32_32x32x16_bf16 v[2:17], v[126:129], v[102:105], v[2:17]
	ds_read_b128 v[102:105], v74 offset:59904
	ds_read_b128 v[134:137], v74 offset:59936
	s_waitcnt lgkmcnt(1)
	v_mfma_f32_32x32x16_bf16 v[50:65], v[94:97], v[102:105], v[50:65]
	global_load_dwordx4 v[94:97], v80, s[2:3] offset:1664
	global_load_dwordx4 v[142:145], v80, s[4:5] offset:1664
	s_waitcnt vmcnt(9)
	ds_write_b128 v75, v[106:109]
	s_waitcnt vmcnt(8)
	ds_write_b128 v75, v[138:141] offset:18432
	v_mfma_f32_32x32x16_bf16 v[18:33], v[126:129], v[102:105], v[18:33]
	global_load_dwordx4 v[102:105], v79, s[2:3] offset:1664
	global_load_dwordx4 v[106:109], v79, s[4:5] offset:1664
	v_mfma_f32_32x32x16_bf16 v[34:49], v[118:121], v[122:125], v[34:49]
	v_mfma_f32_32x32x16_bf16 v[2:17], v[130:133], v[122:125], v[2:17]
	s_waitcnt lgkmcnt(2)
	v_mfma_f32_32x32x16_bf16 v[50:65], v[118:121], v[134:137], v[50:65]
	ds_read_b128 v[118:121], v73 offset:36928
	ds_read_b128 v[122:125], v73 offset:41536
	ds_read_b128 v[126:129], v74 offset:55360
	ds_read_b128 v[138:141], v74 offset:59968
	s_waitcnt vmcnt(9)
	ds_write_b128 v75, v[82:85] offset:4608
	s_waitcnt vmcnt(8)
	ds_write_b128 v75, v[110:113] offset:23040
	v_mfma_f32_32x32x16_bf16 v[18:33], v[130:133], v[134:137], v[18:33]
	global_load_dwordx4 v[82:85], v78, s[2:3] offset:1664
	global_load_dwordx4 v[110:113], v78, s[4:5] offset:1664
	s_waitcnt lgkmcnt(3)
	v_mfma_f32_32x32x16_bf16 v[34:49], v[118:121], v[126:129], v[34:49]
	v_mfma_f32_32x32x16_bf16 v[2:17], v[122:125], v[126:129], v[2:17]
	s_waitcnt lgkmcnt(2)
	v_mfma_f32_32x32x16_bf16 v[50:65], v[118:121], v[138:141], v[50:65]
	ds_read_b128 v[118:121], v73 offset:36960
	ds_read_b128 v[126:129], v73 offset:41568
	ds_read_b128 v[130:133], v74 offset:55392
	ds_read_b128 v[134:137], v74 offset:60000
	s_waitcnt vmcnt(9)
	ds_write_b128 v75, v[86:89] offset:9216
	s_waitcnt vmcnt(8)
	ds_write_b128 v75, v[114:117] offset:27648
	v_mfma_f32_32x32x16_bf16 v[18:33], v[122:125], v[138:141], v[18:33]
	global_load_dwordx4 v[86:89], v77, s[2:3] offset:1664
	global_load_dwordx4 v[114:117], v77, s[4:5] offset:1664
	s_waitcnt lgkmcnt(3)
	v_mfma_f32_32x32x16_bf16 v[34:49], v[118:121], v[130:133], v[34:49]
	s_waitcnt vmcnt(9)
	ds_write_b128 v75, v[90:93] offset:13824
	s_waitcnt vmcnt(8)
	ds_write_b128 v75, v[98:101] offset:32256
	v_mfma_f32_32x32x16_bf16 v[2:17], v[126:129], v[130:133], v[2:17]
	s_waitcnt lgkmcnt(4)
	v_mfma_f32_32x32x16_bf16 v[50:65], v[118:121], v[134:137], v[50:65]
	v_mfma_f32_32x32x16_bf16 v[18:33], v[126:129], v[134:137], v[18:33]
	s_waitcnt lgkmcnt(0)
	s_barrier
	ds_read_b128 v[90:93], v73
	ds_read_b128 v[98:101], v74 offset:18432
	ds_read_b128 v[118:121], v73 offset:32
	ds_read_b128 v[122:125], v74 offset:18464
	ds_read_b128 v[126:129], v73 offset:4608
	ds_read_b128 v[130:133], v73 offset:4640
	s_waitcnt lgkmcnt(4)
	v_mfma_f32_32x32x16_bf16 v[34:49], v[90:93], v[98:101], v[34:49]
	s_waitcnt lgkmcnt(1)
	v_mfma_f32_32x32x16_bf16 v[2:17], v[126:129], v[98:101], v[2:17]
	ds_read_b128 v[98:101], v74 offset:23040
	ds_read_b128 v[134:137], v74 offset:23072
	s_waitcnt lgkmcnt(1)
	v_mfma_f32_32x32x16_bf16 v[50:65], v[90:93], v[98:101], v[50:65]
	global_load_dwordx4 v[90:93], v80, s[2:3] offset:1792
	global_load_dwordx4 v[138:141], v80, s[4:5] offset:1792
	s_waitcnt vmcnt(9)
	ds_write_b128 v75, v[94:97] offset:36864
	s_waitcnt vmcnt(8)
	ds_write_b128 v75, v[142:145] offset:55296
	v_mfma_f32_32x32x16_bf16 v[18:33], v[126:129], v[98:101], v[18:33]
	global_load_dwordx4 v[94:97], v79, s[2:3] offset:1792
	global_load_dwordx4 v[98:101], v79, s[4:5] offset:1792
	v_mfma_f32_32x32x16_bf16 v[34:49], v[118:121], v[122:125], v[34:49]
	v_mfma_f32_32x32x16_bf16 v[2:17], v[130:133], v[122:125], v[2:17]
	s_waitcnt lgkmcnt(2)
	v_mfma_f32_32x32x16_bf16 v[50:65], v[118:121], v[134:137], v[50:65]
	ds_read_b128 v[118:121], v73 offset:64
	ds_read_b128 v[122:125], v73 offset:4672
	ds_read_b128 v[126:129], v74 offset:18496
	ds_read_b128 v[142:145], v74 offset:23104
	s_waitcnt vmcnt(9)
	ds_write_b128 v75, v[102:105] offset:41472
	s_waitcnt vmcnt(8)
	ds_write_b128 v75, v[106:109] offset:59904
	v_mfma_f32_32x32x16_bf16 v[18:33], v[130:133], v[134:137], v[18:33]
	global_load_dwordx4 v[102:105], v78, s[2:3] offset:1792
	global_load_dwordx4 v[106:109], v78, s[4:5] offset:1792
	s_waitcnt lgkmcnt(3)
	v_mfma_f32_32x32x16_bf16 v[34:49], v[118:121], v[126:129], v[34:49]
	v_mfma_f32_32x32x16_bf16 v[2:17], v[122:125], v[126:129], v[2:17]
	s_waitcnt lgkmcnt(2)
	v_mfma_f32_32x32x16_bf16 v[50:65], v[118:121], v[142:145], v[50:65]
	ds_read_b128 v[118:121], v73 offset:96
	ds_read_b128 v[126:129], v73 offset:4704
	ds_read_b128 v[130:133], v74 offset:18528
	ds_read_b128 v[134:137], v74 offset:23136
	s_waitcnt vmcnt(9)
	ds_write_b128 v75, v[82:85] offset:46080
	s_waitcnt vmcnt(8)
	ds_write_b128 v75, v[110:113] offset:64512
	v_mfma_f32_32x32x16_bf16 v[18:33], v[122:125], v[142:145], v[18:33]
	global_load_dwordx4 v[82:85], v77, s[2:3] offset:1792
	global_load_dwordx4 v[110:113], v77, s[4:5] offset:1792
	s_waitcnt lgkmcnt(3)
	v_mfma_f32_32x32x16_bf16 v[34:49], v[118:121], v[130:133], v[34:49]
	s_waitcnt vmcnt(9)
	ds_write_b128 v75, v[86:89] offset:50688
	s_waitcnt vmcnt(8)
	ds_write_b128 v76, v[114:117] offset:13824
	v_mfma_f32_32x32x16_bf16 v[2:17], v[126:129], v[130:133], v[2:17]
	s_waitcnt lgkmcnt(4)
	v_mfma_f32_32x32x16_bf16 v[50:65], v[118:121], v[134:137], v[50:65]
	v_mfma_f32_32x32x16_bf16 v[18:33], v[126:129], v[134:137], v[18:33]
	s_waitcnt lgkmcnt(0)
	s_barrier
; #define GL1_(RA, RB, i) { RA[i] = *(const u32x4*)(ap + (aoff + (i) * astep)); if ((i) < NB) RB[(i) < NB ? (i) : 0] = *(const u32x4*)(bp + (boff + (i) * bstep)); }
; #define LS1_(RA, RB, ST, i) { char* sn_ = lds + (ST) * STAGE; *(u32x4*)(sn_ + wofs + (i) * 32 * LROW) = RA[i]; \
;                               if ((i) < NB) *(u32x4*)(sn_ + STAGE_OP + wofs + (i) * 32 * LROW) = RB[(i) < NB ? (i) : 0]; }
; template <int NJ> DI void gemm_mainloop_reg(const bf16_t* __restrict__ A, int lda, const bf16_t* __restrict__ Bt, int ldb, int K, f32x16 (&acc)[2][NJ], char* lds) {
;     ...
; #pragma unroll
;   for (int i = 0; i < 4; ++i) GL1_(ra0, rb0, i);
;   ap += 128; bp += 128;
; #pragma unroll
;   for (int i = 0; i < 4; ++i) GL1_(ra1, rb1, i);
;   ap += 128; bp += 128;
; #pragma unroll
;   for (int i = 0; i < 4; ++i) LS1_(ra0, rb0, 0, i);
;   __syncthreads();
;   const int nk = K >> 6;
;   for (int kt = 0; kt < nk; kt += 2) {
;     const bool l0 = (kt + 2 < nk), l1 = (kt + 3 < nk);
;     STEP_(0, l0, ra0, rb0, true, ra1, rb1);
;     __syncthreads();
;     STEP_(1, l1, ra1, rb1, l0, ra0, rb0);
;     __syncthreads();
;   }
	ds_read_b128 v[86:89], v73 offset:36864
	ds_read_b128 v[114:117], v74 offset:55296
	ds_read_b128 v[118:121], v73 offset:41472
	s_waitcnt lgkmcnt(1)
	v_mfma_f32_32x32x16_bf16 v[34:49], v[86:89], v[114:117], v[34:49]
	s_waitcnt lgkmcnt(0)
	v_mfma_f32_32x32x16_bf16 v[2:17], v[118:121], v[114:117], v[2:17]
	ds_read_b128 v[114:117], v74 offset:59904
	s_waitcnt lgkmcnt(0)
	v_mfma_f32_32x32x16_bf16 v[50:65], v[86:89], v[114:117], v[50:65]
	global_load_dwordx4 v[86:89], v80, s[2:3] offset:1920
	global_load_dwordx4 v[122:125], v80, s[4:5] offset:1920
	ds_read_b128 v[126:129], v73 offset:36896
	ds_read_b128 v[130:133], v74 offset:55328
	ds_read_b128 v[134:137], v73 offset:41504
	ds_read_b128 v[142:145], v74 offset:59936
	s_waitcnt vmcnt(9)
	ds_write_b128 v75, v[90:93]
	s_waitcnt vmcnt(8)
	ds_write_b128 v75, v[138:141] offset:18432
	v_mfma_f32_32x32x16_bf16 v[18:33], v[118:121], v[114:117], v[18:33]
	global_load_dwordx4 v[90:93], v79, s[2:3] offset:1920
	global_load_dwordx4 v[114:117], v79, s[4:5] offset:1920
	s_waitcnt lgkmcnt(4)
	v_mfma_f32_32x32x16_bf16 v[34:49], v[126:129], v[130:133], v[34:49]
	s_waitcnt lgkmcnt(3)
	v_mfma_f32_32x32x16_bf16 v[2:17], v[134:137], v[130:133], v[2:17]
	s_waitcnt lgkmcnt(2)
	v_mfma_f32_32x32x16_bf16 v[50:65], v[126:129], v[142:145], v[50:65]
	ds_read_b128 v[118:121], v73 offset:36928
	ds_read_b128 v[126:129], v73 offset:41536
	ds_read_b128 v[130:133], v74 offset:55360
	ds_read_b128 v[138:141], v74 offset:59968
	s_waitcnt vmcnt(9)
	ds_write_b128 v75, v[94:97] offset:4608
	s_waitcnt vmcnt(8)
	ds_write_b128 v75, v[98:101] offset:23040
	v_mfma_f32_32x32x16_bf16 v[18:33], v[134:137], v[142:145], v[18:33]
	global_load_dwordx4 v[94:97], v78, s[2:3] offset:1920
	s_nop 0
	global_load_dwordx4 v[78:81], v78, s[4:5] offset:1920
	s_waitcnt lgkmcnt(3)
	v_mfma_f32_32x32x16_bf16 v[34:49], v[118:121], v[130:133], v[34:49]
	v_mfma_f32_32x32x16_bf16 v[2:17], v[126:129], v[130:133], v[2:17]
	s_waitcnt lgkmcnt(2)
	v_mfma_f32_32x32x16_bf16 v[50:65], v[118:121], v[138:141], v[50:65]
	ds_read_b128 v[98:101], v73 offset:36960
	ds_read_b128 v[118:121], v73 offset:41568
	ds_read_b128 v[130:133], v74 offset:55392
	ds_read_b128 v[134:137], v74 offset:60000
	s_waitcnt vmcnt(9)
	ds_write_b128 v75, v[102:105] offset:9216
	s_waitcnt vmcnt(8)
	ds_write_b128 v75, v[106:109] offset:27648
	v_mfma_f32_32x32x16_bf16 v[18:33], v[126:129], v[138:141], v[18:33]
	s_waitcnt lgkmcnt(3)
	v_mfma_f32_32x32x16_bf16 v[34:49], v[98:101], v[130:133], v[34:49]
	s_waitcnt lgkmcnt(2)
	v_mfma_f32_32x32x16_bf16 v[50:65], v[98:101], v[134:137], v[50:65]
	global_load_dwordx4 v[98:101], v77, s[2:3] offset:1920
	global_load_dwordx4 v[102:105], v77, s[4:5] offset:1920
	s_waitcnt vmcnt(9)
	ds_write_b128 v75, v[82:85] offset:13824
	s_waitcnt vmcnt(8)
	ds_write_b128 v75, v[110:113] offset:32256
	v_mfma_f32_32x32x16_bf16 v[2:17], v[118:121], v[130:133], v[2:17]
	v_mfma_f32_32x32x16_bf16 v[18:33], v[118:121], v[134:137], v[18:33]
	s_waitcnt lgkmcnt(0)
	s_barrier
	ds_read_b128 v[82:85], v73
	ds_read_b128 v[106:109], v74 offset:18432
	ds_read_b128 v[110:113], v73 offset:4608
	s_waitcnt lgkmcnt(1)
	v_mfma_f32_32x32x16_bf16 v[34:49], v[82:85], v[106:109], v[34:49]
	s_waitcnt lgkmcnt(0)
	v_mfma_f32_32x32x16_bf16 v[2:17], v[110:113], v[106:109], v[2:17]
	ds_read_b128 v[106:109], v74 offset:23040
	s_waitcnt lgkmcnt(0)
	v_mfma_f32_32x32x16_bf16 v[50:65], v[82:85], v[106:109], v[50:65]
	ds_read_b128 v[82:85], v73 offset:32
	ds_read_b128 v[118:121], v74 offset:18464
	ds_read_b128 v[126:129], v73 offset:4640
	ds_read_b128 v[130:133], v74 offset:23072
	s_waitcnt vmcnt(7)
	ds_write_b128 v75, v[86:89] offset:36864
	s_waitcnt vmcnt(6)
	ds_write_b128 v75, v[122:125] offset:55296
	v_mfma_f32_32x32x16_bf16 v[18:33], v[110:113], v[106:109], v[18:33]
	s_waitcnt lgkmcnt(4)
	v_mfma_f32_32x32x16_bf16 v[34:49], v[82:85], v[118:121], v[34:49]
	s_waitcnt lgkmcnt(2)
	v_mfma_f32_32x32x16_bf16 v[50:65], v[82:85], v[130:133], v[50:65]
	ds_read_b128 v[82:85], v73 offset:64
	ds_read_b128 v[86:89], v73 offset:4672
	ds_read_b128 v[106:109], v74 offset:18496
	ds_read_b128 v[110:113], v74 offset:23104
	s_waitcnt vmcnt(5)
	ds_write_b128 v75, v[90:93] offset:41472
	s_waitcnt vmcnt(4)
	ds_write_b128 v75, v[114:117] offset:59904
	v_mfma_f32_32x32x16_bf16 v[2:17], v[126:129], v[118:121], v[2:17]
	v_mfma_f32_32x32x16_bf16 v[18:33], v[126:129], v[130:133], v[18:33]
	s_waitcnt lgkmcnt(3)
	v_mfma_f32_32x32x16_bf16 v[34:49], v[82:85], v[106:109], v[34:49]
	v_mfma_f32_32x32x16_bf16 v[2:17], v[86:89], v[106:109], v[2:17]
	s_waitcnt lgkmcnt(2)
	v_mfma_f32_32x32x16_bf16 v[50:65], v[82:85], v[110:113], v[50:65]
	ds_read_b128 v[82:85], v73 offset:96
	ds_read_b128 v[90:93], v73 offset:4704
	ds_read_b128 v[106:109], v74 offset:18528
	ds_read_b128 v[114:117], v74 offset:23136
	s_waitcnt vmcnt(3)
	ds_write_b128 v75, v[94:97] offset:46080
	s_waitcnt vmcnt(2)
	ds_write_b128 v75, v[78:81] offset:64512
	v_mfma_f32_32x32x16_bf16 v[18:33], v[86:89], v[110:113], v[18:33]
	s_waitcnt lgkmcnt(3)
	v_mfma_f32_32x32x16_bf16 v[34:49], v[82:85], v[106:109], v[34:49]
	s_waitcnt vmcnt(1)
	ds_write_b128 v75, v[98:101] offset:50688
	s_waitcnt vmcnt(0)
	ds_write_b128 v76, v[102:105] offset:13824
	v_mfma_f32_32x32x16_bf16 v[2:17], v[90:93], v[106:109], v[2:17]
	s_waitcnt lgkmcnt(4)
	v_mfma_f32_32x32x16_bf16 v[50:65], v[82:85], v[114:117], v[50:65]
	v_mfma_f32_32x32x16_bf16 v[18:33], v[90:93], v[114:117], v[18:33]
	s_waitcnt lgkmcnt(0)
	s_barrier
; DI int tid_() { int t = threadIdx.x; asm volatile("" : "+v"(t)); return t; }
; template <int NJ> DI void acc_to_lds(const f32x16 (&acc)[2][NJ], float* cl) {
;   const int tid = tid_(), lane = tid & 63, w = tid >> 6, wm = w >> 1, wn = w & 1, h = lane >> 5, c = lane & 31;
; #pragma unroll
;   for (int i = 0; i < 2; ++i)
; #pragma unroll
;     for (int j = 0; j < NJ; ++j)
; #pragma unroll
;       for (int r = 0; r < 16; ++r) {
;         const int row = wm * 64 + i * 32 + (r & 3) + 8 * (r >> 2) + 4 * h;
;         cl[row * CLD + wn * 32 * NJ + j * 32 + c] = acc[i][j][r];
;       }
; }
; DI void phase_ffn_in(const Ctx& c, const bf16_t* A, size_t woff, int site) {
;     ...
;     f32x16 acc[2][2]; zero_acc<2>(acc);
;     gemm_mainloop_reg<2>(A + (size_t)mt * 128 * LDX, LDX, Bt + (size_t)nt * 128 * LDX, LDX, DM, acc, c.lds);
;     acc_to_lds<2>(acc, cl);
;     if (tid < 128) rr[tid] = rsqrtf(ss[mt * 128 + tid] * (1.0f / DM) + EPS);
	ds_read_b128 v[76:79], v73 offset:36864
	ds_read_b128 v[80:83], v74 offset:55296
	ds_read_b128 v[84:87], v73 offset:41472
	s_waitcnt lgkmcnt(1)
	v_mfma_f32_32x32x16_bf16 v[34:49], v[76:79], v[80:83], v[34:49]
	s_waitcnt lgkmcnt(0)
	v_mfma_f32_32x32x16_bf16 v[2:17], v[84:87], v[80:83], v[2:17]
	ds_read_b128 v[80:83], v74 offset:59904
	s_waitcnt lgkmcnt(0)
	v_mfma_f32_32x32x16_bf16 v[50:65], v[76:79], v[80:83], v[50:65]
	ds_read_b128 v[76:79], v73 offset:36896
	ds_read_b128 v[88:91], v74 offset:55328
	ds_read_b128 v[92:95], v73 offset:41504
	ds_read_b128 v[96:99], v74 offset:59936
	v_mfma_f32_32x32x16_bf16 v[18:33], v[84:87], v[80:83], v[18:33]
	s_waitcnt lgkmcnt(2)
	v_mfma_f32_32x32x16_bf16 v[34:49], v[76:79], v[88:91], v[34:49]
	s_waitcnt lgkmcnt(1)
	v_mfma_f32_32x32x16_bf16 v[2:17], v[92:95], v[88:91], v[2:17]
	s_waitcnt lgkmcnt(0)
	v_mfma_f32_32x32x16_bf16 v[50:65], v[76:79], v[96:99], v[50:65]
	ds_read_b128 v[76:79], v73 offset:36928
	ds_read_b128 v[80:83], v73 offset:41536
	ds_read_b128 v[84:87], v74 offset:55360
	ds_read_b128 v[88:91], v74 offset:59968
	v_mfma_f32_32x32x16_bf16 v[18:33], v[92:95], v[96:99], v[18:33]
	s_waitcnt lgkmcnt(1)
	v_mfma_f32_32x32x16_bf16 v[34:49], v[76:79], v[84:87], v[34:49]
	v_mfma_f32_32x32x16_bf16 v[2:17], v[80:83], v[84:87], v[2:17]
	s_waitcnt lgkmcnt(0)
	v_mfma_f32_32x32x16_bf16 v[50:65], v[76:79], v[88:91], v[50:65]
	ds_read_b128 v[76:79], v73 offset:36960
	ds_read_b128 v[84:87], v73 offset:41568
	ds_read_b128 v[92:95], v74 offset:55392
	ds_read_b128 v[96:99], v74 offset:60000
	v_mfma_f32_32x32x16_bf16 v[18:33], v[80:83], v[88:91], v[18:33]
	s_waitcnt lgkmcnt(1)
	v_mfma_f32_32x32x16_bf16 v[34:49], v[76:79], v[92:95], v[34:49]
	v_mfma_f32_32x32x16_bf16 v[2:17], v[84:87], v[92:95], v[2:17]
	s_waitcnt lgkmcnt(0)
	v_mfma_f32_32x32x16_bf16 v[50:65], v[76:79], v[96:99], v[50:65]
	v_mfma_f32_32x32x16_bf16 v[18:33], v[84:87], v[96:99], v[18:33]
	s_setprio 0
	s_nop 0
	v_mov_b32_e32 v73, v199
	s_barrier
	s_nop 0
	v_lshrrev_b32_e32 v75, 3, v73
	v_lshrrev_b32_e32 v74, 1, v73
	v_and_b32_e32 v75, 4, v75
	v_and_b32_e32 v73, 0x5f, v73
	v_and_or_b32 v74, v74, s17, v75
	v_mul_lo_u32 v74, v74, s15
	v_lshlrev_b32_e32 v73, 2, v73
	v_add3_u32 v73, 0, v74, v73
	ds_write2_b32 v73, v34, v50 offset1:32
	ds_write2_b32 v73, v35, v51 offset0:132 offset1:164
	v_add_u32_e32 v34, 0x400, v73
	ds_write2_b32 v34, v36, v52 offset0:8 offset1:40
	ds_write2_b32 v34, v37, v53 offset0:140 offset1:172
	v_add_u32_e32 v34, 0x1000, v73
	ds_write2_b32 v34, v38, v54 offset0:32 offset1:64
	ds_write2_b32 v34, v39, v55 offset0:164 offset1:196
	v_add_u32_e32 v34, 0x1400, v73
	ds_write2_b32 v34, v40, v56 offset0:40 offset1:72
	ds_write2_b32 v34, v41, v57 offset0:172 offset1:204
	v_add_u32_e32 v34, 0x2000, v73
	ds_write2_b32 v34, v42, v58 offset0:64 offset1:96
	ds_write2_b32 v34, v43, v59 offset0:196 offset1:228
	v_add_u32_e32 v34, 0x2400, v73
	ds_write2_b32 v34, v44, v60 offset0:72 offset1:104
	ds_write2_b32 v34, v45, v61 offset0:204 offset1:236
	v_add_u32_e32 v34, 0x3000, v73
	ds_write2_b32 v34, v46, v62 offset0:96 offset1:128
	v_add_u32_e32 v34, 0x3200, v73
	ds_write2_b32 v34, v47, v63 offset0:100 offset1:132
	v_add_u32_e32 v34, 0x3400, v73
	ds_write2_b32 v34, v48, v64 offset0:104 offset1:136
	v_add_u32_e32 v34, 0x3600, v73
	ds_write2_b32 v34, v49, v65 offset0:108 offset1:140
	v_add_u32_e32 v34, 0x4000, v73
	ds_write2_b32 v34, v2, v18 offset0:128 offset1:160
	v_add_u32_e32 v2, 0x4400, v73
	ds_write2_b32 v2, v3, v19 offset0:4 offset1:36
	ds_write2_b32 v2, v4, v20 offset0:136 offset1:168
	v_add_u32_e32 v2, 0x4800, v73
	ds_write2_b32 v2, v5, v21 offset0:12 offset1:44
	v_add_u32_e32 v2, 0x5000, v73
	ds_write2_b32 v2, v6, v22 offset0:160 offset1:192
	v_add_u32_e32 v2, 0x5400, v73
	ds_write2_b32 v2, v7, v23 offset0:36 offset1:68
	ds_write2_b32 v2, v8, v24 offset0:168 offset1:200
	v_add_u32_e32 v2, 0x5800, v73
	ds_write2_b32 v2, v9, v25 offset0:44 offset1:76
	v_add_u32_e32 v2, 0x6000, v73
	ds_write2_b32 v2, v10, v26 offset0:192 offset1:224
	v_add_u32_e32 v2, 0x6400, v73
	ds_write2_b32 v2, v11, v27 offset0:68 offset1:100
	ds_write2_b32 v2, v12, v28 offset0:200 offset1:232
	v_add_u32_e32 v2, 0x6800, v73
	ds_write2_b32 v2, v13, v29 offset0:76 offset1:108
	v_add_u32_e32 v2, 0x7200, v73
	ds_write2_b32 v2, v14, v30 offset0:96 offset1:128
	v_add_u32_e32 v2, 0x7400, v73
	ds_write2_b32 v2, v15, v31 offset0:100 offset1:132
	v_add_u32_e32 v2, 0x7600, v73
	ds_write2_b32 v2, v16, v32 offset0:104 offset1:136
	v_add_u32_e32 v2, 0x7800, v73
	ds_write2_b32 v2, v17, v33 offset0:108 offset1:140
	s_and_saveexec_b64 s[2:3], s[38:39]
	s_cbranch_execz .LBB0_1098
	v_lshl_add_u32 v2, s36, 7, v68
	v_ashrrev_i32_e32 v3, 31, v2
	v_lshl_add_u64 v[2:3], v[2:3], 2, s[0:1]
	v_mov_b32_e32 v2, v253
	s_nop 0
	s_mov_b32 s4, 0x800000
	s_waitcnt vmcnt(0)
	v_fmamk_f32 v2, v2, 0x3a800000, v198
	v_mul_f32_e32 v3, 0x4b800000, v2
	v_cmp_gt_f32_e32 vcc, s4, v2
	s_nop 1
	v_cndmask_b32_e32 v2, v2, v3, vcc
	v_rsq_f32_e32 v2, v2
	s_nop 0
	v_mul_f32_e32 v3, 0x45800000, v2
	v_cndmask_b32_e32 v2, v2, v3, vcc
	ds_write_b32 v69, v2
